# v47 + second-K-slice tile loads reuse the first slice's address pair with offset:128 (M0 set 128 lower), 22 v_lshl_add_u64 dropped
# speedup vs baseline: 1.0079x; 1.0079x over previous
; #define PG8_STAGE(bufoff, gbase, voff) do { _Pragma("unroll") for (int _i = 0; _i < 2; ++_i) \
;         __builtin_amdgcn_global_load_lds((const unsigned*)((const char*)(gbase) + (voff)[_i]), (LAS unsigned*)(lds + (bufoff) + ldsw + _i * 8192), 16, 0, 0); } while (0)
; #define PG8_LDA(dst, b, h) do { _Pragma("unroll") for (int m = 0; m < 4; ++m) _Pragma("unroll") for (int k = 0; k < 2; ++k) dst[m][k] = *(const LAS bf16x8*)(lds + PG8_SA(b, h) + aoff + m * 2048 + k * 1024); } while (0)
; #define PG8_LDB(dst, b, h) do { _Pragma("unroll") for (int n = 0; n < 2; ++n) _Pragma("unroll") for (int k = 0; k < 2; ++k) dst[n][k] = *(const LAS bf16x8*)(lds + PG8_SB(b, h) + boff + n * 2048 + k * 1024); } while (0)
; #define PG8_MMA(ai, bj, At, Bt) do { __builtin_amdgcn_s_setprio(1); _Pragma("unroll") for (int m = 0; m < 4; ++m) _Pragma("unroll") for (int n = 0; n < 2; ++n) _Pragma("unroll") for (int k = 0; k < 2; ++k) \
;         acc[ai][bj][m][n] = __builtin_amdgcn_mfma_f32_16x16x32_bf16(Bt[n][k], At[m][k], acc[ai][bj][m][n], 0, 0, 0); __builtin_amdgcn_s_setprio(0); } while (0)
; #define PG8_WAIT_V(n) asm volatile("s_waitcnt vmcnt(" #n ")" ::: "memory")
; #define PG8_WAIT_L(n) asm volatile("s_waitcnt lgkmcnt(" #n ")" ::: "memory")
; #define PG8_BAR __builtin_amdgcn_s_barrier()
; #define PG8_SCHED __builtin_amdgcn_sched_barrier(0)
; template <class Epi, class Sched>
; __device__ __forceinline__ void gemm_phase(LAS unsigned char* lds, const Gemm g, const Sched& S, const Epi& E) {
;     ...
;             const bool last = (t == nt - 2);
;             const char* a1 = cA + (size_t)(t + 1) * kstep;
;             const char* a2 = last ? nA : cA + (size_t)(t + 2) * kstep; const char* b2 = last ? nB : cB + (size_t)(t + 2) * kstep;
;             const char* a3 = a2 + kstep; const char* b3 = b2 + kstep;
;             if (last && has_next) S.a_ready(nxt);
;             PG8_LDB(B0, 0, 0); PG8_LDB(B1, 0, 1); PG8_SCHED; PG8_LDA(At, 0, 0); PG8_STAGE(PG8_SA(1, 1), a1 + hstepA, voffA);
;             PG8_WAIT_V(8); PG8_WAIT_L(0); PG8_BAR; PG8_MMA(0, 0, At, B0); PG8_MMA(0, 1, At, B1); PG8_BAR; PG8_SCHED;
;             PG8_LDA(At, 0, 1); PG8_STAGE(PG8_SB(0, 0), b2, voffB); PG8_STAGE(PG8_SB(0, 1), b2 + hstepB, voffB); PG8_STAGE(PG8_SA(0, 0), a2, voffA);
.LBB0_137:
	s_add_u32 s28, s26, 0xfff80080
	s_addc_u32 s29, s27, -1
	s_add_i32 s60, 0, 0x10000
	s_cmp_eq_u32 s59, 28
	s_cselect_b32 s41, s21, s29
	s_cselect_b32 s40, s55, s28
	s_cselect_b32 s29, s19, s58
	s_cselect_b32 s28, s56, s57
	s_add_i32 s62, 0, 0x14000
	v_add_u32_e32 v154, s60, v159
	v_add_u32_e32 v174, s62, v159
	ds_read_b128 v[142:145], v154
	ds_read_b128 v[146:149], v154 offset:1024
	ds_read_b128 v[150:153], v154 offset:2048
	ds_read_b128 v[154:157], v154 offset:3072
	ds_read_b128 v[162:165], v174
	ds_read_b128 v[166:169], v174 offset:1024
	ds_read_b128 v[170:173], v174 offset:2048
	ds_read_b128 v[174:177], v174 offset:3072
	s_add_i32 m0, s46, 0xc000
	ds_read_b128 v[178:181], v161
	ds_read_b128 v[182:185], v161 offset:1024
	ds_read_b128 v[186:189], v161 offset:2048
	ds_read_b128 v[190:193], v161 offset:3072
	ds_read_b128 v[194:197], v161 offset:4096
	ds_read_b128 v[212:215], v161 offset:5120
	ds_read_b128 v[216:219], v161 offset:6144
	ds_read_b128 v[220:223], v161 offset:7168
	global_load_lds_dwordx4 v138, s[26:27]
	s_add_i32 m0, s46, 0xe000
	s_nop 0
	global_load_lds_dwordx4 v140, s[26:27]
	s_waitcnt vmcnt(8)
	s_waitcnt lgkmcnt(0)
	s_barrier
	s_waitcnt lgkmcnt(0)
	v_mfma_f32_16x16x32_bf16 v[130:133], v[142:145], v[178:181], v[130:133]
	v_mfma_f32_16x16x32_bf16 v[122:125], v[150:153], v[178:181], v[122:125]
	v_mfma_f32_16x16x32_bf16 v[114:117], v[142:145], v[186:189], v[114:117]
	v_mfma_f32_16x16x32_bf16 v[106:109], v[150:153], v[186:189], v[106:109]
	v_mfma_f32_16x16x32_bf16 v[98:101], v[142:145], v[194:197], v[98:101]
	v_mfma_f32_16x16x32_bf16 v[90:93], v[150:153], v[194:197], v[90:93]
	v_mfma_f32_16x16x32_bf16 v[82:85], v[142:145], v[216:219], v[82:85]
	v_mfma_f32_16x16x32_bf16 v[74:77], v[150:153], v[216:219], v[74:77]
	v_mfma_f32_16x16x32_bf16 v[130:133], v[146:149], v[182:185], v[130:133]
	v_mfma_f32_16x16x32_bf16 v[122:125], v[154:157], v[182:185], v[122:125]
	v_mfma_f32_16x16x32_bf16 v[114:117], v[146:149], v[190:193], v[114:117]
	v_mfma_f32_16x16x32_bf16 v[106:109], v[154:157], v[190:193], v[106:109]
	v_mfma_f32_16x16x32_bf16 v[98:101], v[146:149], v[212:215], v[98:101]
	v_mfma_f32_16x16x32_bf16 v[90:93], v[154:157], v[212:215], v[90:93]
	v_mfma_f32_16x16x32_bf16 v[82:85], v[146:149], v[220:223], v[82:85]
	v_mfma_f32_16x16x32_bf16 v[74:77], v[154:157], v[220:223], v[74:77]
	v_mfma_f32_16x16x32_bf16 v[126:129], v[162:165], v[178:181], v[126:129]
	v_mfma_f32_16x16x32_bf16 v[118:121], v[170:173], v[178:181], v[118:121]
	v_mfma_f32_16x16x32_bf16 v[110:113], v[162:165], v[186:189], v[110:113]
	v_mfma_f32_16x16x32_bf16 v[102:105], v[170:173], v[186:189], v[102:105]
	v_mfma_f32_16x16x32_bf16 v[94:97], v[162:165], v[194:197], v[94:97]
	v_mfma_f32_16x16x32_bf16 v[86:89], v[170:173], v[194:197], v[86:89]
	v_mfma_f32_16x16x32_bf16 v[78:81], v[162:165], v[216:219], v[78:81]
	v_mfma_f32_16x16x32_bf16 v[70:73], v[170:173], v[216:219], v[70:73]
	v_mfma_f32_16x16x32_bf16 v[126:129], v[166:169], v[182:185], v[126:129]
	v_mfma_f32_16x16x32_bf16 v[118:121], v[174:177], v[182:185], v[118:121]
	v_mfma_f32_16x16x32_bf16 v[110:113], v[166:169], v[190:193], v[110:113]
	v_mfma_f32_16x16x32_bf16 v[102:105], v[174:177], v[190:193], v[102:105]
	v_mfma_f32_16x16x32_bf16 v[94:97], v[166:169], v[212:215], v[94:97]
	v_mfma_f32_16x16x32_bf16 v[86:89], v[174:177], v[212:215], v[86:89]
	v_mfma_f32_16x16x32_bf16 v[78:81], v[166:169], v[220:223], v[78:81]
	v_mfma_f32_16x16x32_bf16 v[70:73], v[174:177], v[220:223], v[70:73]
	s_barrier
	s_add_i32 s60, s60, s45
	v_lshl_add_u64 v[224:225], s[28:29], 0, v[4:5]
	s_mov_b32 m0, s60
	ds_read_b128 v[178:181], v161 offset:16384
	ds_read_b128 v[182:185], v161 offset:17408
	ds_read_b128 v[186:189], v161 offset:18432
	ds_read_b128 v[190:193], v161 offset:19456
	ds_read_b128 v[194:197], v161 offset:20480
	ds_read_b128 v[212:215], v161 offset:21504
	ds_read_b128 v[216:219], v161 offset:22528
	ds_read_b128 v[220:223], v161 offset:23552
	global_load_lds_dwordx4 v[224:225], off
	s_add_i32 m0, s60, 0x2000
	s_add_u32 s60, s28, 0x80000
	v_lshl_add_u64 v[226:227], s[28:29], 0, v[2:3]
	s_addc_u32 s61, s29, 0
	s_add_i32 s62, s62, s45
	global_load_lds_dwordx4 v[226:227], off
	s_mov_b32 m0, s62
	v_lshl_add_u64 v[230:231], s[40:41], 0, v[134:135]
	global_load_lds_dwordx4 v4, s[60:61]
	s_add_i32 m0, s62, 0x2000
	s_nop 0
	global_load_lds_dwordx4 v2, s[60:61]
	v_lshl_add_u64 v[228:229], s[40:41], 0, v[136:137]
	s_mov_b32 m0, s46
	s_nop 0
	global_load_lds_dwordx4 v[228:229], off
	s_mov_b32 m0, s47
	s_nop 0
	global_load_lds_dwordx4 v[230:231], off
	s_waitcnt vmcnt(8)
	s_waitcnt lgkmcnt(0)
	s_barrier
; #define PG8_STAGE(bufoff, gbase, voff) do { _Pragma("unroll") for (int _i = 0; _i < 2; ++_i) \
;         __builtin_amdgcn_global_load_lds((const unsigned*)((const char*)(gbase) + (voff)[_i]), (LAS unsigned*)(lds + (bufoff) + ldsw + _i * 8192), 16, 0, 0); } while (0)
; #define PG8_LDA(dst, b, h) do { _Pragma("unroll") for (int m = 0; m < 4; ++m) _Pragma("unroll") for (int k = 0; k < 2; ++k) dst[m][k] = *(const LAS bf16x8*)(lds + PG8_SA(b, h) + aoff + m * 2048 + k * 1024); } while (0)
; #define PG8_LDB(dst, b, h) do { _Pragma("unroll") for (int n = 0; n < 2; ++n) _Pragma("unroll") for (int k = 0; k < 2; ++k) dst[n][k] = *(const LAS bf16x8*)(lds + PG8_SB(b, h) + boff + n * 2048 + k * 1024); } while (0)
; #define PG8_MMA(ai, bj, At, Bt) do { __builtin_amdgcn_s_setprio(1); _Pragma("unroll") for (int m = 0; m < 4; ++m) _Pragma("unroll") for (int n = 0; n < 2; ++n) _Pragma("unroll") for (int k = 0; k < 2; ++k) \
;         acc[ai][bj][m][n] = __builtin_amdgcn_mfma_f32_16x16x32_bf16(Bt[n][k], At[m][k], acc[ai][bj][m][n], 0, 0, 0); __builtin_amdgcn_s_setprio(0); } while (0)
; #define PG8_WAIT_V(n) asm volatile("s_waitcnt vmcnt(" #n ")" ::: "memory")
; #define PG8_WAIT_L(n) asm volatile("s_waitcnt lgkmcnt(" #n ")" ::: "memory")
; #define PG8_BAR __builtin_amdgcn_s_barrier()
; #define PG8_SCHED __builtin_amdgcn_sched_barrier(0)
; template <class Epi, class Sched>
; __device__ __forceinline__ void gemm_phase(LAS unsigned char* lds, const Gemm g, const Sched& S, const Epi& E) {
;     ...
;             PG8_WAIT_V(8); PG8_WAIT_L(0); PG8_BAR; PG8_MMA(1, 0, At, B0); PG8_MMA(1, 1, At, B1); PG8_BAR; PG8_SCHED;
;             PG8_LDB(B0, 1, 0); PG8_LDB(B1, 1, 1); PG8_SCHED; PG8_LDA(At, 1, 0); PG8_STAGE(PG8_SA(0, 1), a2 + hstepA, voffA);
;             PG8_WAIT_V(8); PG8_WAIT_L(0); PG8_BAR; PG8_MMA(0, 0, At, B0); PG8_MMA(0, 1, At, B1); PG8_BAR; PG8_SCHED;
	s_waitcnt lgkmcnt(0)
	v_mfma_f32_16x16x32_bf16 v[66:69], v[142:145], v[178:181], v[66:69]
	v_mfma_f32_16x16x32_bf16 v[58:61], v[150:153], v[178:181], v[58:61]
	v_mfma_f32_16x16x32_bf16 v[50:53], v[142:145], v[186:189], v[50:53]
	v_mfma_f32_16x16x32_bf16 v[42:45], v[150:153], v[186:189], v[42:45]
	v_mfma_f32_16x16x32_bf16 v[34:37], v[142:145], v[194:197], v[34:37]
	v_mfma_f32_16x16x32_bf16 v[26:29], v[150:153], v[194:197], v[26:29]
	v_mfma_f32_16x16x32_bf16 v[18:21], v[142:145], v[216:219], v[18:21]
	v_mfma_f32_16x16x32_bf16 v[10:13], v[150:153], v[216:219], v[10:13]
	v_mfma_f32_16x16x32_bf16 v[66:69], v[146:149], v[182:185], v[66:69]
	v_mfma_f32_16x16x32_bf16 v[58:61], v[154:157], v[182:185], v[58:61]
	v_mfma_f32_16x16x32_bf16 v[50:53], v[146:149], v[190:193], v[50:53]
	v_mfma_f32_16x16x32_bf16 v[42:45], v[154:157], v[190:193], v[42:45]
	v_mfma_f32_16x16x32_bf16 v[34:37], v[146:149], v[212:215], v[34:37]
	v_mfma_f32_16x16x32_bf16 v[26:29], v[154:157], v[212:215], v[26:29]
	v_mfma_f32_16x16x32_bf16 v[18:21], v[146:149], v[220:223], v[18:21]
	v_mfma_f32_16x16x32_bf16 v[10:13], v[154:157], v[220:223], v[10:13]
	v_mfma_f32_16x16x32_bf16 v[62:65], v[162:165], v[178:181], v[62:65]
	v_mfma_f32_16x16x32_bf16 v[54:57], v[170:173], v[178:181], v[54:57]
	v_mfma_f32_16x16x32_bf16 v[46:49], v[162:165], v[186:189], v[46:49]
	v_mfma_f32_16x16x32_bf16 v[38:41], v[170:173], v[186:189], v[38:41]
	v_mfma_f32_16x16x32_bf16 v[30:33], v[162:165], v[194:197], v[30:33]
	v_mfma_f32_16x16x32_bf16 v[22:25], v[170:173], v[194:197], v[22:25]
	v_mfma_f32_16x16x32_bf16 v[14:17], v[162:165], v[216:219], v[14:17]
	v_mfma_f32_16x16x32_bf16 v[6:9], v[170:173], v[216:219], v[6:9]
	v_mfma_f32_16x16x32_bf16 v[62:65], v[166:169], v[182:185], v[62:65]
	v_mfma_f32_16x16x32_bf16 v[54:57], v[174:177], v[182:185], v[54:57]
	v_mfma_f32_16x16x32_bf16 v[46:49], v[166:169], v[190:193], v[46:49]
	v_mfma_f32_16x16x32_bf16 v[38:41], v[174:177], v[190:193], v[38:41]
	v_mfma_f32_16x16x32_bf16 v[30:33], v[166:169], v[212:215], v[30:33]
	v_mfma_f32_16x16x32_bf16 v[22:25], v[174:177], v[212:215], v[22:25]
	v_mfma_f32_16x16x32_bf16 v[14:17], v[166:169], v[220:223], v[14:17]
	v_mfma_f32_16x16x32_bf16 v[6:9], v[174:177], v[220:223], v[6:9]
	s_barrier
	s_add_i32 s60, 0, 0x18000
	s_add_i32 s61, 0, 0x1c000
	v_add_u32_e32 v154, s60, v159
	v_add_u32_e32 v174, s61, v159
	ds_read_b128 v[142:145], v154
	ds_read_b128 v[146:149], v154 offset:1024
	ds_read_b128 v[150:153], v154 offset:2048
	ds_read_b128 v[154:157], v154 offset:3072
	ds_read_b128 v[162:165], v174
	ds_read_b128 v[166:169], v174 offset:1024
	ds_read_b128 v[170:173], v174 offset:2048
	ds_read_b128 v[174:177], v174 offset:3072
	s_add_u32 s40, s40, 0x80000
	s_addc_u32 s41, s41, 0
	s_mov_b32 m0, s48
	ds_read_b128 v[178:181], v161 offset:32768
	ds_read_b128 v[182:185], v161 offset:33792
	ds_read_b128 v[186:189], v161 offset:34816
	ds_read_b128 v[190:193], v161 offset:35840
	ds_read_b128 v[194:197], v161 offset:36864
	ds_read_b128 v[212:215], v161 offset:37888
	ds_read_b128 v[216:219], v161 offset:38912
	ds_read_b128 v[220:223], v161 offset:39936
	global_load_lds_dwordx4 v136, s[40:41]
	s_mov_b32 m0, s49
	s_nop 0
	global_load_lds_dwordx4 v134, s[40:41]
	s_waitcnt vmcnt(8)
	s_waitcnt lgkmcnt(0)
	s_barrier
	s_waitcnt lgkmcnt(0)
	v_mfma_f32_16x16x32_bf16 v[130:133], v[142:145], v[178:181], v[130:133]
	v_mfma_f32_16x16x32_bf16 v[122:125], v[150:153], v[178:181], v[122:125]
	v_mfma_f32_16x16x32_bf16 v[114:117], v[142:145], v[186:189], v[114:117]
	v_mfma_f32_16x16x32_bf16 v[106:109], v[150:153], v[186:189], v[106:109]
	v_mfma_f32_16x16x32_bf16 v[98:101], v[142:145], v[194:197], v[98:101]
	v_mfma_f32_16x16x32_bf16 v[90:93], v[150:153], v[194:197], v[90:93]
	v_mfma_f32_16x16x32_bf16 v[82:85], v[142:145], v[216:219], v[82:85]
	v_mfma_f32_16x16x32_bf16 v[74:77], v[150:153], v[216:219], v[74:77]
	v_mfma_f32_16x16x32_bf16 v[130:133], v[146:149], v[182:185], v[130:133]
	v_mfma_f32_16x16x32_bf16 v[122:125], v[154:157], v[182:185], v[122:125]
	v_mfma_f32_16x16x32_bf16 v[114:117], v[146:149], v[190:193], v[114:117]
	v_mfma_f32_16x16x32_bf16 v[106:109], v[154:157], v[190:193], v[106:109]
	v_mfma_f32_16x16x32_bf16 v[98:101], v[146:149], v[212:215], v[98:101]
	v_mfma_f32_16x16x32_bf16 v[90:93], v[154:157], v[212:215], v[90:93]
	v_mfma_f32_16x16x32_bf16 v[82:85], v[146:149], v[220:223], v[82:85]
	v_mfma_f32_16x16x32_bf16 v[74:77], v[154:157], v[220:223], v[74:77]
	v_mfma_f32_16x16x32_bf16 v[126:129], v[162:165], v[178:181], v[126:129]
	v_mfma_f32_16x16x32_bf16 v[118:121], v[170:173], v[178:181], v[118:121]
	v_mfma_f32_16x16x32_bf16 v[110:113], v[162:165], v[186:189], v[110:113]
	v_mfma_f32_16x16x32_bf16 v[102:105], v[170:173], v[186:189], v[102:105]
	v_mfma_f32_16x16x32_bf16 v[94:97], v[162:165], v[194:197], v[94:97]
	v_mfma_f32_16x16x32_bf16 v[86:89], v[170:173], v[194:197], v[86:89]
	v_mfma_f32_16x16x32_bf16 v[78:81], v[162:165], v[216:219], v[78:81]
	v_mfma_f32_16x16x32_bf16 v[70:73], v[170:173], v[216:219], v[70:73]
	v_mfma_f32_16x16x32_bf16 v[126:129], v[166:169], v[182:185], v[126:129]
	v_mfma_f32_16x16x32_bf16 v[118:121], v[174:177], v[182:185], v[118:121]
	v_mfma_f32_16x16x32_bf16 v[110:113], v[166:169], v[190:193], v[110:113]
	v_mfma_f32_16x16x32_bf16 v[102:105], v[174:177], v[190:193], v[102:105]
	v_mfma_f32_16x16x32_bf16 v[94:97], v[166:169], v[212:215], v[94:97]
	v_mfma_f32_16x16x32_bf16 v[86:89], v[174:177], v[212:215], v[86:89]
	v_mfma_f32_16x16x32_bf16 v[78:81], v[166:169], v[220:223], v[78:81]
	v_mfma_f32_16x16x32_bf16 v[70:73], v[174:177], v[220:223], v[70:73]
	s_barrier
; #define PG8_STAGE(bufoff, gbase, voff) do { _Pragma("unroll") for (int _i = 0; _i < 2; ++_i) \
;         __builtin_amdgcn_global_load_lds((const unsigned*)((const char*)(gbase) + (voff)[_i]), (LAS unsigned*)(lds + (bufoff) + ldsw + _i * 8192), 16, 0, 0); } while (0)
; #define PG8_LDA(dst, b, h) do { _Pragma("unroll") for (int m = 0; m < 4; ++m) _Pragma("unroll") for (int k = 0; k < 2; ++k) dst[m][k] = *(const LAS bf16x8*)(lds + PG8_SA(b, h) + aoff + m * 2048 + k * 1024); } while (0)
; #define PG8_MMA(ai, bj, At, Bt) do { __builtin_amdgcn_s_setprio(1); _Pragma("unroll") for (int m = 0; m < 4; ++m) _Pragma("unroll") for (int n = 0; n < 2; ++n) _Pragma("unroll") for (int k = 0; k < 2; ++k) \
;         acc[ai][bj][m][n] = __builtin_amdgcn_mfma_f32_16x16x32_bf16(Bt[n][k], At[m][k], acc[ai][bj][m][n], 0, 0, 0); __builtin_amdgcn_s_setprio(0); } while (0)
; #define PG8_WAIT_V(n) asm volatile("s_waitcnt vmcnt(" #n ")" ::: "memory")
; #define PG8_WAIT_L(n) asm volatile("s_waitcnt lgkmcnt(" #n ")" ::: "memory")
; #define PG8_BAR __builtin_amdgcn_s_barrier()
; #define PG8_SCHED __builtin_amdgcn_sched_barrier(0)
; template <class Epi, class Sched>
; __device__ __forceinline__ void gemm_phase(LAS unsigned char* lds, const Gemm g, const Sched& S, const Epi& E) {
;     ...
;             PG8_LDA(At, 1, 1); PG8_STAGE(PG8_SB(1, 0), b3, voffB); PG8_STAGE(PG8_SB(1, 1), b3 + hstepB, voffB); PG8_STAGE(PG8_SA(1, 0), a3, voffA);
;             PG8_WAIT_V(8); PG8_WAIT_L(0); PG8_BAR; PG8_MMA(1, 0, At, B0); PG8_MMA(1, 1, At, B1); PG8_BAR; PG8_SCHED;
;         }
	s_add_i32 s40, s60, s45
	s_add_i32 m0, s40, 0xffffff80
	ds_read_b128 v[178:181], v161 offset:49152
	ds_read_b128 v[182:185], v161 offset:50176
	ds_read_b128 v[186:189], v161 offset:51200
	ds_read_b128 v[190:193], v161 offset:52224
	ds_read_b128 v[194:197], v161 offset:53248
	ds_read_b128 v[212:215], v161 offset:54272
	ds_read_b128 v[216:219], v161 offset:55296
	ds_read_b128 v[220:223], v161 offset:56320
	global_load_lds_dwordx4 v[224:225], off offset:128
	s_add_i32 m0, s40, 0x1f80
	s_add_u32 s28, s28, 0x80080
	s_addc_u32 s29, s29, 0
	s_add_i32 s40, s61, s45
	global_load_lds_dwordx4 v[226:227], off offset:128
	s_mov_b32 m0, s40
	s_nop 0
	global_load_lds_dwordx4 v4, s[28:29]
	s_add_i32 m0, s40, 0x2000
	s_nop 0
	global_load_lds_dwordx4 v2, s[28:29]
	s_add_i32 m0, s50, 0xffffff80
	s_nop 0
	global_load_lds_dwordx4 v[228:229], off offset:128
	s_add_i32 m0, s51, 0xffffff80
	s_nop 0
	global_load_lds_dwordx4 v[230:231], off offset:128
	s_waitcnt vmcnt(8)
	s_waitcnt lgkmcnt(0)
	s_barrier
	s_waitcnt lgkmcnt(0)
	v_mfma_f32_16x16x32_bf16 v[66:69], v[142:145], v[178:181], v[66:69]
	v_mfma_f32_16x16x32_bf16 v[58:61], v[150:153], v[178:181], v[58:61]
	v_mfma_f32_16x16x32_bf16 v[50:53], v[142:145], v[186:189], v[50:53]
	v_mfma_f32_16x16x32_bf16 v[42:45], v[150:153], v[186:189], v[42:45]
	v_mfma_f32_16x16x32_bf16 v[34:37], v[142:145], v[194:197], v[34:37]
	v_mfma_f32_16x16x32_bf16 v[26:29], v[150:153], v[194:197], v[26:29]
	v_mfma_f32_16x16x32_bf16 v[18:21], v[142:145], v[216:219], v[18:21]
	v_mfma_f32_16x16x32_bf16 v[10:13], v[150:153], v[216:219], v[10:13]
	v_mfma_f32_16x16x32_bf16 v[66:69], v[146:149], v[182:185], v[66:69]
	v_mfma_f32_16x16x32_bf16 v[58:61], v[154:157], v[182:185], v[58:61]
	v_mfma_f32_16x16x32_bf16 v[50:53], v[146:149], v[190:193], v[50:53]
	v_mfma_f32_16x16x32_bf16 v[42:45], v[154:157], v[190:193], v[42:45]
	v_mfma_f32_16x16x32_bf16 v[34:37], v[146:149], v[212:215], v[34:37]
	v_mfma_f32_16x16x32_bf16 v[26:29], v[154:157], v[212:215], v[26:29]
	v_mfma_f32_16x16x32_bf16 v[18:21], v[146:149], v[220:223], v[18:21]
	v_mfma_f32_16x16x32_bf16 v[10:13], v[154:157], v[220:223], v[10:13]
	v_mfma_f32_16x16x32_bf16 v[62:65], v[162:165], v[178:181], v[62:65]
	v_mfma_f32_16x16x32_bf16 v[54:57], v[170:173], v[178:181], v[54:57]
	v_mfma_f32_16x16x32_bf16 v[46:49], v[162:165], v[186:189], v[46:49]
	v_mfma_f32_16x16x32_bf16 v[38:41], v[170:173], v[186:189], v[38:41]
	v_mfma_f32_16x16x32_bf16 v[30:33], v[162:165], v[194:197], v[30:33]
	v_mfma_f32_16x16x32_bf16 v[22:25], v[170:173], v[194:197], v[22:25]
	v_mfma_f32_16x16x32_bf16 v[14:17], v[162:165], v[216:219], v[14:17]
	v_mfma_f32_16x16x32_bf16 v[6:9], v[170:173], v[216:219], v[6:9]
	v_mfma_f32_16x16x32_bf16 v[62:65], v[166:169], v[182:185], v[62:65]
	v_mfma_f32_16x16x32_bf16 v[54:57], v[174:177], v[182:185], v[54:57]
	v_mfma_f32_16x16x32_bf16 v[46:49], v[166:169], v[190:193], v[46:49]
	v_mfma_f32_16x16x32_bf16 v[38:41], v[174:177], v[190:193], v[38:41]
	v_mfma_f32_16x16x32_bf16 v[30:33], v[166:169], v[212:215], v[30:33]
	v_mfma_f32_16x16x32_bf16 v[22:25], v[174:177], v[212:215], v[22:25]
	v_mfma_f32_16x16x32_bf16 v[14:17], v[166:169], v[220:223], v[14:17]
	v_mfma_f32_16x16x32_bf16 v[6:9], v[174:177], v[220:223], v[6:9]
	s_barrier
	s_add_i32 s59, s59, 2
	s_add_u32 s26, s26, 0x100
	s_addc_u32 s27, s27, 0
	s_add_u32 s57, s57, 0x100
	s_addc_u32 s58, s58, 0
	s_cmp_gt_u32 s59, 29
	s_cbranch_scc0 .LBB0_137
	s_and_b64 vcc, exec, s[16:17]
	s_cbranch_vccz .LBB0_140
	s_barrier

; #define PG8_STAGE(bufoff, gbase, voff) do { _Pragma("unroll") for (int _i = 0; _i < 2; ++_i) \
;         __builtin_amdgcn_global_load_lds((const unsigned*)((const char*)(gbase) + (voff)[_i]), (LAS unsigned*)(lds + (bufoff) + ldsw + _i * 8192), 16, 0, 0); } while (0)
; #define PG8_WAIT_V(n) asm volatile("s_waitcnt vmcnt(" #n ")" ::: "memory")
; #define PG8_BAR __builtin_amdgcn_s_barrier()
; template <class Epi, class Sched>
; __device__ __forceinline__ void gemm_phase(LAS unsigned char* lds, const Gemm g, const Sched& S, const Epi& E) {
;     ...
;     f32x4 acc[2][2][4][2];
; #pragma unroll
;     for (int a = 0; a < 2; ++a)
; #pragma unroll
;         for (int b = 0; b < 2; ++b)
; #pragma unroll
;             for (int m = 0; m < 4; ++m)
; #pragma unroll
;                 for (int n = 0; n < 2; ++n) acc[a][b][m][n] = (f32x4){0.f, 0.f, 0.f, 0.f};
;     bf16x8 At[4][2], B0[2][2], B1[2][2];
;     const char* cA = (const char*)g.A + (size_t)cur.pm * tstepA + (size_t)cur.ka * 2; const char* cB = (const char*)g.Bt + (size_t)cur.pn * tstepB;
;     S.a_ready(cur);
;     PG8_STAGE(PG8_SB(0, 0), cB, voffB); PG8_STAGE(PG8_SB(0, 1), cB + hstepB, voffB); PG8_STAGE(PG8_SA(0, 0), cA, voffA); PG8_STAGE(PG8_SA(0, 1), cA + hstepA, voffA);
;     if (wr == 1) PG8_BAR;
;     PG8_WAIT_V(2); PG8_BAR;
;     PG8_STAGE(PG8_SB(1, 0), cB + kstep, voffB); PG8_STAGE(PG8_SA(1, 0), cA + kstep, voffA); PG8_STAGE(PG8_SB(1, 1), cB + hstepB + kstep, voffB);
;     PG8_WAIT_V(6); PG8_BAR;
.LBB0_267:
	v_lshl_add_u64 v[14:15], s[24:25], 0, v[4:5]
	v_mov_b32_e32 v3, v5
	v_and_b32_e32 v142, 15, v143
	v_and_b32_e32 v22, 48, v143
	v_lshlrev_b32_e32 v23, 2, v143
	v_lshl_add_u64 v[16:17], s[24:25], 0, v[2:3]
	s_and_b32 s48, s44, 3
	v_lshl_or_b32 v22, v142, 6, v22
	s_lshl_b32 s4, s47, 13
	v_and_b32_e32 v23, 32, v23
	s_add_i32 m0, s50, 0x18000
	v_lshl_add_u64 v[14:15], v[14:15], 0, s[36:37]
	v_lshl_add_u64 v[18:19], s[20:21], 0, v[4:5]
	v_bitop3_b32 v24, v22, s4, v23 bitop3:0xde
	s_lshl_b32 s4, s48, 12
	s_waitcnt vmcnt(2)
	s_barrier
	global_load_lds_dwordx4 v[14:15], off
	v_lshl_add_u64 v[14:15], v[16:17], 0, s[36:37]
	s_add_i32 m0, s50, 0x1a000
	s_add_i32 s54, s50, 0x8000
	s_add_i32 s55, s50, 0xa000
	v_lshl_add_u64 v[20:21], s[20:21], 0, v[2:3]
	v_bitop3_b32 v144, v22, s4, v23 bitop3:0xde
	global_load_lds_dwordx4 v[14:15], off
	v_lshl_add_u64 v[14:15], v[18:19], 0, s[36:37]
	s_mov_b32 m0, s54
	s_add_u32 s4, s24, 0x158080
	global_load_lds_dwordx4 v[14:15], off
	v_lshl_add_u64 v[14:15], v[20:21], 0, s[36:37]
	s_mov_b32 m0, s55
	s_addc_u32 s5, s25, 0
	global_load_lds_dwordx4 v[14:15], off
	s_add_i32 m0, s50, 0x1c000
	v_lshl_add_u64 v[14:15], s[4:5], 0, v[4:5]
	global_load_lds_dwordx4 v[14:15], off
	v_lshl_add_u64 v[14:15], s[4:5], 0, v[2:3]
	s_add_i32 m0, s50, 0x1e000
	s_movk_i32 s10, 0x1580
	global_load_lds_dwordx4 v[14:15], off
	v_lshrrev_b32_e32 v11, 1, v11
	v_mul_lo_u32 v10, v10, s10
	s_mov_b32 s22, 0x15800
	v_mad_u64_u32 v[10:11], s[4:5], v11, s22, v[10:11]
	v_or_b32_e32 v10, v10, v12
	v_add_lshl_u32 v134, v10, v13, 1
	v_lshrrev_b32_e32 v10, 1, v6
	v_mul_lo_u32 v6, v7, s10
	v_mad_u64_u32 v[6:7], s[4:5], v10, s22, v[6:7]
	s_waitcnt vmcnt(6)
	v_or_b32_e32 v6, v6, v8
	s_cmpk_lt_u32 s45, 0x100
	v_add_lshl_u32 v136, v6, v9, 1
	v_mov_b32_e32 v6, 0
	v_readlane_b32 s4, v254, 13
	s_cselect_b64 s[18:19], -1, 0
	v_mov_b32_e32 v135, v5
	v_mov_b32_e32 v137, v5
	s_mov_b32 s59, 0
	v_add_u32_e32 v145, 0, v24
	s_mov_b32 s10, s4
	v_readlane_b32 s46, v253, 61
	v_mov_b32_e32 v7, v6
	v_mov_b32_e32 v8, v6
	v_mov_b32_e32 v9, v6
	v_mov_b32_e32 v10, v6
	v_mov_b32_e32 v11, v6
	v_mov_b32_e32 v12, v6
	v_mov_b32_e32 v13, v6
	v_mov_b32_e32 v14, v6
	v_mov_b32_e32 v15, v6
	v_mov_b32_e32 v16, v6
	v_mov_b32_e32 v17, v6
	v_mov_b32_e32 v18, v6
	v_mov_b32_e32 v19, v6
	v_mov_b32_e32 v20, v6
	v_mov_b32_e32 v21, v6
	v_mov_b32_e32 v22, v6
	v_mov_b32_e32 v23, v6
	v_mov_b32_e32 v24, v6
	v_mov_b32_e32 v25, v6
	v_mov_b32_e32 v30, v6
	v_mov_b32_e32 v31, v6
	v_mov_b32_e32 v32, v6
	v_mov_b32_e32 v33, v6
	v_mov_b32_e32 v38, v6
	v_mov_b32_e32 v39, v6
	v_mov_b32_e32 v40, v6
	v_mov_b32_e32 v41, v6
	v_mov_b32_e32 v46, v6
	v_mov_b32_e32 v47, v6
	v_mov_b32_e32 v48, v6
	v_mov_b32_e32 v49, v6
	v_mov_b32_e32 v26, v6
	v_mov_b32_e32 v27, v6
	v_mov_b32_e32 v28, v6
	v_mov_b32_e32 v29, v6
	v_mov_b32_e32 v34, v6
	v_mov_b32_e32 v35, v6
	v_mov_b32_e32 v36, v6
	v_mov_b32_e32 v37, v6
	v_mov_b32_e32 v42, v6
	v_mov_b32_e32 v43, v6
	v_mov_b32_e32 v44, v6
	v_mov_b32_e32 v45, v6
	v_mov_b32_e32 v50, v6
	v_mov_b32_e32 v51, v6
	v_mov_b32_e32 v52, v6
	v_mov_b32_e32 v53, v6
	v_mov_b32_e32 v54, v6
	v_mov_b32_e32 v55, v6
	v_mov_b32_e32 v56, v6
	v_mov_b32_e32 v57, v6
	v_mov_b32_e32 v58, v6
	v_mov_b32_e32 v59, v6
	v_mov_b32_e32 v60, v6
	v_mov_b32_e32 v61, v6
	v_mov_b32_e32 v62, v6
	v_mov_b32_e32 v63, v6
	v_mov_b32_e32 v64, v6
	v_mov_b32_e32 v65, v6
	v_mov_b32_e32 v66, v6
	v_mov_b32_e32 v67, v6
	v_mov_b32_e32 v68, v6
	v_mov_b32_e32 v69, v6
	v_mov_b32_e32 v70, v6
	v_mov_b32_e32 v71, v6
	v_mov_b32_e32 v72, v6
	v_mov_b32_e32 v73, v6
	v_mov_b32_e32 v74, v6
	v_mov_b32_e32 v75, v6
	v_mov_b32_e32 v76, v6
	v_mov_b32_e32 v77, v6
	v_mov_b32_e32 v78, v6
	v_mov_b32_e32 v79, v6
	v_mov_b32_e32 v80, v6
	v_mov_b32_e32 v81, v6
	v_mov_b32_e32 v82, v6
	v_mov_b32_e32 v83, v6
	v_mov_b32_e32 v84, v6
	v_mov_b32_e32 v85, v6
	v_mov_b32_e32 v86, v6
	v_mov_b32_e32 v87, v6
	v_mov_b32_e32 v88, v6
	v_mov_b32_e32 v89, v6
	v_mov_b32_e32 v94, v6
	v_mov_b32_e32 v95, v6
	v_mov_b32_e32 v96, v6
	v_mov_b32_e32 v97, v6
	v_mov_b32_e32 v102, v6
	v_mov_b32_e32 v103, v6
	v_mov_b32_e32 v104, v6
	v_mov_b32_e32 v105, v6
	v_mov_b32_e32 v114, v6
	v_mov_b32_e32 v115, v6
	v_mov_b32_e32 v116, v6
	v_mov_b32_e32 v117, v6
	v_mov_b32_e32 v90, v6
	v_mov_b32_e32 v91, v6
	v_mov_b32_e32 v92, v6
	v_mov_b32_e32 v93, v6
	v_mov_b32_e32 v98, v6
	v_mov_b32_e32 v99, v6
	v_mov_b32_e32 v100, v6
	v_mov_b32_e32 v101, v6
	v_mov_b32_e32 v106, v6
	v_mov_b32_e32 v107, v6
	v_mov_b32_e32 v108, v6
	v_mov_b32_e32 v109, v6
	v_mov_b32_e32 v110, v6
	v_mov_b32_e32 v111, v6
	v_mov_b32_e32 v112, v6
	v_mov_b32_e32 v113, v6
	v_mov_b32_e32 v118, v6
	v_mov_b32_e32 v119, v6
	v_mov_b32_e32 v120, v6
	v_mov_b32_e32 v121, v6
	v_mov_b32_e32 v122, v6
	v_mov_b32_e32 v123, v6
	v_mov_b32_e32 v124, v6
	v_mov_b32_e32 v125, v6
	v_mov_b32_e32 v126, v6
	v_mov_b32_e32 v127, v6
	v_mov_b32_e32 v128, v6
	v_mov_b32_e32 v129, v6
	v_mov_b32_e32 v130, v6
	v_mov_b32_e32 v131, v6
	v_mov_b32_e32 v132, v6
	v_mov_b32_e32 v133, v6
	s_barrier
	s_branch .LBB0_270
	s_nop 0
	s_nop 0
	s_nop 0
	s_nop 0
	s_nop 0
	s_nop 0
	s_nop 0
	s_nop 0
	s_nop 0
	s_nop 0
	s_nop 0
	s_nop 0
.LBB0_268:
	s_mov_b64 s[22:23], s[24:25]
	s_mov_b64 s[4:5], s[20:21]
	s_mov_b32 s58, s59
	s_andn2_b64 vcc, exec, s[38:39]
	s_cbranch_vccz .LBB0_288

; #define PG8_STAGE(bufoff, gbase, voff) do { _Pragma("unroll") for (int _i = 0; _i < 2; ++_i) \
;         __builtin_amdgcn_global_load_lds((const unsigned*)((const char*)(gbase) + (voff)[_i]), (LAS unsigned*)(lds + (bufoff) + ldsw + _i * 8192), 16, 0, 0); } while (0)
; #define PG8_LDA(dst, b, h) do { _Pragma("unroll") for (int m = 0; m < 4; ++m) _Pragma("unroll") for (int k = 0; k < 2; ++k) dst[m][k] = *(const LAS bf16x8*)(lds + PG8_SA(b, h) + aoff + m * 2048 + k * 1024); } while (0)
; #define PG8_LDB(dst, b, h) do { _Pragma("unroll") for (int n = 0; n < 2; ++n) _Pragma("unroll") for (int k = 0; k < 2; ++k) dst[n][k] = *(const LAS bf16x8*)(lds + PG8_SB(b, h) + boff + n * 2048 + k * 1024); } while (0)
; #define PG8_MMA(ai, bj, At, Bt) do { __builtin_amdgcn_s_setprio(1); _Pragma("unroll") for (int m = 0; m < 4; ++m) _Pragma("unroll") for (int n = 0; n < 2; ++n) _Pragma("unroll") for (int k = 0; k < 2; ++k) \
;         acc[ai][bj][m][n] = __builtin_amdgcn_mfma_f32_16x16x32_bf16(Bt[n][k], At[m][k], acc[ai][bj][m][n], 0, 0, 0); __builtin_amdgcn_s_setprio(0); } while (0)
; #define PG8_WAIT_V(n) asm volatile("s_waitcnt vmcnt(" #n ")" ::: "memory")
; #define PG8_WAIT_L(n) asm volatile("s_waitcnt lgkmcnt(" #n ")" ::: "memory")
; #define PG8_BAR __builtin_amdgcn_s_barrier()
; #define PG8_SCHED __builtin_amdgcn_sched_barrier(0)
; template <class Epi, class Sched>
; __device__ __forceinline__ void gemm_phase(LAS unsigned char* lds, const Gemm g, const Sched& S, const Epi& E) {
;     ...
;             const bool last = (t == nt - 2);
;             const char* a1 = cA + (size_t)(t + 1) * kstep;
;             const char* a2 = last ? nA : cA + (size_t)(t + 2) * kstep; const char* b2 = last ? nB : cB + (size_t)(t + 2) * kstep;
;             const char* a3 = a2 + kstep; const char* b3 = b2 + kstep;
;             if (last && has_next) S.a_ready(nxt);
;             PG8_LDB(B0, 0, 0); PG8_LDB(B1, 0, 1); PG8_SCHED; PG8_LDA(At, 0, 0); PG8_STAGE(PG8_SA(1, 1), a1 + hstepA, voffA);
;             PG8_WAIT_V(8); PG8_WAIT_L(0); PG8_BAR; PG8_MMA(0, 0, At, B0); PG8_MMA(0, 1, At, B1); PG8_BAR; PG8_SCHED;
;             PG8_LDA(At, 0, 1); PG8_STAGE(PG8_SB(0, 0), b2, voffB); PG8_STAGE(PG8_SB(0, 1), b2 + hstepB, voffB); PG8_STAGE(PG8_SA(0, 0), a2, voffA);
.LBB0_281:
	s_add_u32 s26, s20, s24
	s_addc_u32 s27, s21, s25
	s_add_u32 s26, s26, 0x100
	s_addc_u32 s27, s27, 0
	s_add_u32 s63, s60, s24
	s_addc_u32 s65, s61, s25
	s_add_i32 s67, 0, 0x10000
	s_cmpk_eq_i32 s24, 0x2a00
	s_cselect_b32 s29, s5, s27
	s_cselect_b32 s28, s4, s26
	s_cselect_b32 s27, s23, s65
	s_cselect_b32 s26, s22, s63
	s_add_i32 s63, 0, 0x14000
	v_add_u32_e32 v158, s67, v144
	v_add_u32_e32 v174, s63, v144
	ds_read_b128 v[146:149], v158
	ds_read_b128 v[150:153], v158 offset:1024
	ds_read_b128 v[154:157], v158 offset:2048
	ds_read_b128 v[158:161], v158 offset:3072
	ds_read_b128 v[162:165], v174
	ds_read_b128 v[166:169], v174 offset:1024
	ds_read_b128 v[170:173], v174 offset:2048
	ds_read_b128 v[174:177], v174 offset:3072
	v_lshl_add_u64 v[224:225], v[138:139], 0, s[24:25]
	s_add_i32 m0, s50, 0xc000
	ds_read_b128 v[178:181], v145
	ds_read_b128 v[182:185], v145 offset:1024
	ds_read_b128 v[186:189], v145 offset:2048
	ds_read_b128 v[190:193], v145 offset:3072
	ds_read_b128 v[194:197], v145 offset:4096
	ds_read_b128 v[212:215], v145 offset:5120
	ds_read_b128 v[216:219], v145 offset:6144
	ds_read_b128 v[220:223], v145 offset:7168
	global_load_lds_dwordx4 v[224:225], off
	v_lshl_add_u64 v[224:225], v[140:141], 0, s[24:25]
	s_add_i32 m0, s50, 0xe000
	s_nop 0
	global_load_lds_dwordx4 v[224:225], off
	s_waitcnt vmcnt(8)
	s_waitcnt lgkmcnt(0)
	s_barrier
	s_waitcnt lgkmcnt(0)
	v_mfma_f32_16x16x32_bf16 v[130:133], v[146:149], v[178:181], v[130:133]
	v_mfma_f32_16x16x32_bf16 v[126:129], v[154:157], v[178:181], v[126:129]
	v_mfma_f32_16x16x32_bf16 v[122:125], v[146:149], v[186:189], v[122:125]
	v_mfma_f32_16x16x32_bf16 v[118:121], v[154:157], v[186:189], v[118:121]
	v_mfma_f32_16x16x32_bf16 v[110:113], v[146:149], v[194:197], v[110:113]
	v_mfma_f32_16x16x32_bf16 v[106:109], v[154:157], v[194:197], v[106:109]
	v_mfma_f32_16x16x32_bf16 v[98:101], v[146:149], v[216:219], v[98:101]
	v_mfma_f32_16x16x32_bf16 v[90:93], v[154:157], v[216:219], v[90:93]
	v_mfma_f32_16x16x32_bf16 v[130:133], v[150:153], v[182:185], v[130:133]
	v_mfma_f32_16x16x32_bf16 v[126:129], v[158:161], v[182:185], v[126:129]
	v_mfma_f32_16x16x32_bf16 v[122:125], v[150:153], v[190:193], v[122:125]
	v_mfma_f32_16x16x32_bf16 v[118:121], v[158:161], v[190:193], v[118:121]
	v_mfma_f32_16x16x32_bf16 v[110:113], v[150:153], v[212:215], v[110:113]
	v_mfma_f32_16x16x32_bf16 v[106:109], v[158:161], v[212:215], v[106:109]
	v_mfma_f32_16x16x32_bf16 v[98:101], v[150:153], v[220:223], v[98:101]
	v_mfma_f32_16x16x32_bf16 v[90:93], v[158:161], v[220:223], v[90:93]
	v_mfma_f32_16x16x32_bf16 v[114:117], v[162:165], v[178:181], v[114:117]
	v_mfma_f32_16x16x32_bf16 v[102:105], v[170:173], v[178:181], v[102:105]
	v_mfma_f32_16x16x32_bf16 v[94:97], v[162:165], v[186:189], v[94:97]
	v_mfma_f32_16x16x32_bf16 v[86:89], v[170:173], v[186:189], v[86:89]
	v_mfma_f32_16x16x32_bf16 v[82:85], v[162:165], v[194:197], v[82:85]
	v_mfma_f32_16x16x32_bf16 v[78:81], v[170:173], v[194:197], v[78:81]
	v_mfma_f32_16x16x32_bf16 v[74:77], v[162:165], v[216:219], v[74:77]
	v_mfma_f32_16x16x32_bf16 v[70:73], v[170:173], v[216:219], v[70:73]
	v_mfma_f32_16x16x32_bf16 v[114:117], v[166:169], v[182:185], v[114:117]
	v_mfma_f32_16x16x32_bf16 v[102:105], v[174:177], v[182:185], v[102:105]
	v_mfma_f32_16x16x32_bf16 v[94:97], v[166:169], v[190:193], v[94:97]
	v_mfma_f32_16x16x32_bf16 v[86:89], v[174:177], v[190:193], v[86:89]
	v_mfma_f32_16x16x32_bf16 v[82:85], v[166:169], v[212:215], v[82:85]
	v_mfma_f32_16x16x32_bf16 v[78:81], v[174:177], v[212:215], v[78:81]
	v_mfma_f32_16x16x32_bf16 v[74:77], v[166:169], v[220:223], v[74:77]
	v_mfma_f32_16x16x32_bf16 v[70:73], v[174:177], v[220:223], v[70:73]
	s_barrier
	s_add_i32 s65, s67, s11
	v_lshl_add_u64 v[224:225], s[26:27], 0, v[4:5]
	s_mov_b32 m0, s65
	ds_read_b128 v[178:181], v145 offset:16384
	ds_read_b128 v[182:185], v145 offset:17408
	ds_read_b128 v[186:189], v145 offset:18432
	ds_read_b128 v[190:193], v145 offset:19456
	ds_read_b128 v[194:197], v145 offset:20480
	ds_read_b128 v[212:215], v145 offset:21504
	ds_read_b128 v[216:219], v145 offset:22528
	ds_read_b128 v[220:223], v145 offset:23552
	global_load_lds_dwordx4 v[224:225], off
	s_add_i32 m0, s65, 0x2000
	s_add_u32 s68, s26, 0x158000
	v_lshl_add_u64 v[226:227], s[26:27], 0, v[2:3]
	s_addc_u32 s69, s27, 0
	s_add_i32 s63, s63, s11
	global_load_lds_dwordx4 v[226:227], off
	s_mov_b32 m0, s63
	v_lshl_add_u64 v[230:231], s[28:29], 0, v[2:3]
	global_load_lds_dwordx4 v4, s[68:69]
	s_add_i32 m0, s63, 0x2000
	s_nop 0
	global_load_lds_dwordx4 v2, s[68:69]
	v_lshl_add_u64 v[228:229], s[28:29], 0, v[4:5]
	s_mov_b32 m0, s50
	s_nop 0
	global_load_lds_dwordx4 v[228:229], off
	s_mov_b32 m0, s51
	s_nop 0
	global_load_lds_dwordx4 v[230:231], off
	s_waitcnt vmcnt(8)
	s_waitcnt lgkmcnt(0)
	s_barrier
; #define PG8_STAGE(bufoff, gbase, voff) do { _Pragma("unroll") for (int _i = 0; _i < 2; ++_i) \
;         __builtin_amdgcn_global_load_lds((const unsigned*)((const char*)(gbase) + (voff)[_i]), (LAS unsigned*)(lds + (bufoff) + ldsw + _i * 8192), 16, 0, 0); } while (0)
; #define PG8_LDA(dst, b, h) do { _Pragma("unroll") for (int m = 0; m < 4; ++m) _Pragma("unroll") for (int k = 0; k < 2; ++k) dst[m][k] = *(const LAS bf16x8*)(lds + PG8_SA(b, h) + aoff + m * 2048 + k * 1024); } while (0)
; #define PG8_LDB(dst, b, h) do { _Pragma("unroll") for (int n = 0; n < 2; ++n) _Pragma("unroll") for (int k = 0; k < 2; ++k) dst[n][k] = *(const LAS bf16x8*)(lds + PG8_SB(b, h) + boff + n * 2048 + k * 1024); } while (0)
; #define PG8_MMA(ai, bj, At, Bt) do { __builtin_amdgcn_s_setprio(1); _Pragma("unroll") for (int m = 0; m < 4; ++m) _Pragma("unroll") for (int n = 0; n < 2; ++n) _Pragma("unroll") for (int k = 0; k < 2; ++k) \
;         acc[ai][bj][m][n] = __builtin_amdgcn_mfma_f32_16x16x32_bf16(Bt[n][k], At[m][k], acc[ai][bj][m][n], 0, 0, 0); __builtin_amdgcn_s_setprio(0); } while (0)
; #define PG8_WAIT_V(n) asm volatile("s_waitcnt vmcnt(" #n ")" ::: "memory")
; #define PG8_WAIT_L(n) asm volatile("s_waitcnt lgkmcnt(" #n ")" ::: "memory")
; #define PG8_BAR __builtin_amdgcn_s_barrier()
; #define PG8_SCHED __builtin_amdgcn_sched_barrier(0)
; template <class Epi, class Sched>
; __device__ __forceinline__ void gemm_phase(LAS unsigned char* lds, const Gemm g, const Sched& S, const Epi& E) {
;     ...
;             PG8_WAIT_V(8); PG8_WAIT_L(0); PG8_BAR; PG8_MMA(1, 0, At, B0); PG8_MMA(1, 1, At, B1); PG8_BAR; PG8_SCHED;
;             PG8_LDB(B0, 1, 0); PG8_LDB(B1, 1, 1); PG8_SCHED; PG8_LDA(At, 1, 0); PG8_STAGE(PG8_SA(0, 1), a2 + hstepA, voffA);
;             PG8_WAIT_V(8); PG8_WAIT_L(0); PG8_BAR; PG8_MMA(0, 0, At, B0); PG8_MMA(0, 1, At, B1); PG8_BAR; PG8_SCHED;
	s_waitcnt lgkmcnt(0)
	v_mfma_f32_16x16x32_bf16 v[66:69], v[146:149], v[178:181], v[66:69]
	v_mfma_f32_16x16x32_bf16 v[62:65], v[154:157], v[178:181], v[62:65]
	v_mfma_f32_16x16x32_bf16 v[58:61], v[146:149], v[186:189], v[58:61]
	v_mfma_f32_16x16x32_bf16 v[54:57], v[154:157], v[186:189], v[54:57]
	v_mfma_f32_16x16x32_bf16 v[50:53], v[146:149], v[194:197], v[50:53]
	v_mfma_f32_16x16x32_bf16 v[42:45], v[154:157], v[194:197], v[42:45]
	v_mfma_f32_16x16x32_bf16 v[34:37], v[146:149], v[216:219], v[34:37]
	v_mfma_f32_16x16x32_bf16 v[26:29], v[154:157], v[216:219], v[26:29]
	v_mfma_f32_16x16x32_bf16 v[66:69], v[150:153], v[182:185], v[66:69]
	v_mfma_f32_16x16x32_bf16 v[62:65], v[158:161], v[182:185], v[62:65]
	v_mfma_f32_16x16x32_bf16 v[58:61], v[150:153], v[190:193], v[58:61]
	v_mfma_f32_16x16x32_bf16 v[54:57], v[158:161], v[190:193], v[54:57]
	v_mfma_f32_16x16x32_bf16 v[50:53], v[150:153], v[212:215], v[50:53]
	v_mfma_f32_16x16x32_bf16 v[42:45], v[158:161], v[212:215], v[42:45]
	v_mfma_f32_16x16x32_bf16 v[34:37], v[150:153], v[220:223], v[34:37]
	v_mfma_f32_16x16x32_bf16 v[26:29], v[158:161], v[220:223], v[26:29]
	v_mfma_f32_16x16x32_bf16 v[46:49], v[162:165], v[178:181], v[46:49]
	v_mfma_f32_16x16x32_bf16 v[38:41], v[170:173], v[178:181], v[38:41]
	v_mfma_f32_16x16x32_bf16 v[30:33], v[162:165], v[186:189], v[30:33]
	v_mfma_f32_16x16x32_bf16 v[22:25], v[170:173], v[186:189], v[22:25]
	v_mfma_f32_16x16x32_bf16 v[18:21], v[162:165], v[194:197], v[18:21]
	v_mfma_f32_16x16x32_bf16 v[14:17], v[170:173], v[194:197], v[14:17]
	v_mfma_f32_16x16x32_bf16 v[10:13], v[162:165], v[216:219], v[10:13]
	v_mfma_f32_16x16x32_bf16 v[6:9], v[170:173], v[216:219], v[6:9]
	v_mfma_f32_16x16x32_bf16 v[46:49], v[166:169], v[182:185], v[46:49]
	v_mfma_f32_16x16x32_bf16 v[38:41], v[174:177], v[182:185], v[38:41]
	v_mfma_f32_16x16x32_bf16 v[30:33], v[166:169], v[190:193], v[30:33]
	v_mfma_f32_16x16x32_bf16 v[22:25], v[174:177], v[190:193], v[22:25]
	v_mfma_f32_16x16x32_bf16 v[18:21], v[166:169], v[212:215], v[18:21]
	v_mfma_f32_16x16x32_bf16 v[14:17], v[174:177], v[212:215], v[14:17]
	v_mfma_f32_16x16x32_bf16 v[10:13], v[166:169], v[220:223], v[10:13]
	v_mfma_f32_16x16x32_bf16 v[6:9], v[174:177], v[220:223], v[6:9]
	s_barrier
	s_add_i32 s63, 0, 0x18000
	s_add_i32 s65, 0, 0x1c000
	v_add_u32_e32 v158, s63, v144
	v_add_u32_e32 v174, s65, v144
	ds_read_b128 v[146:149], v158
	ds_read_b128 v[150:153], v158 offset:1024
	ds_read_b128 v[154:157], v158 offset:2048
	ds_read_b128 v[158:161], v158 offset:3072
	ds_read_b128 v[162:165], v174
	ds_read_b128 v[166:169], v174 offset:1024
	ds_read_b128 v[170:173], v174 offset:2048
	ds_read_b128 v[174:177], v174 offset:3072
	s_add_u32 s28, s28, 0x158000
	s_addc_u32 s29, s29, 0
	s_mov_b32 m0, s52
	ds_read_b128 v[178:181], v145 offset:32768
	ds_read_b128 v[182:185], v145 offset:33792
	ds_read_b128 v[186:189], v145 offset:34816
	ds_read_b128 v[190:193], v145 offset:35840
	ds_read_b128 v[194:197], v145 offset:36864
	ds_read_b128 v[212:215], v145 offset:37888
	ds_read_b128 v[216:219], v145 offset:38912
	ds_read_b128 v[220:223], v145 offset:39936
	global_load_lds_dwordx4 v4, s[28:29]
	s_mov_b32 m0, s53
	s_nop 0
	global_load_lds_dwordx4 v2, s[28:29]
	s_waitcnt vmcnt(8)
	s_waitcnt lgkmcnt(0)
	s_barrier
	s_waitcnt lgkmcnt(0)
	v_mfma_f32_16x16x32_bf16 v[130:133], v[146:149], v[178:181], v[130:133]
	v_mfma_f32_16x16x32_bf16 v[126:129], v[154:157], v[178:181], v[126:129]
	v_mfma_f32_16x16x32_bf16 v[122:125], v[146:149], v[186:189], v[122:125]
	v_mfma_f32_16x16x32_bf16 v[118:121], v[154:157], v[186:189], v[118:121]
	v_mfma_f32_16x16x32_bf16 v[110:113], v[146:149], v[194:197], v[110:113]
	v_mfma_f32_16x16x32_bf16 v[106:109], v[154:157], v[194:197], v[106:109]
	v_mfma_f32_16x16x32_bf16 v[98:101], v[146:149], v[216:219], v[98:101]
	v_mfma_f32_16x16x32_bf16 v[90:93], v[154:157], v[216:219], v[90:93]
	v_mfma_f32_16x16x32_bf16 v[130:133], v[150:153], v[182:185], v[130:133]
	v_mfma_f32_16x16x32_bf16 v[126:129], v[158:161], v[182:185], v[126:129]
	v_mfma_f32_16x16x32_bf16 v[122:125], v[150:153], v[190:193], v[122:125]
	v_mfma_f32_16x16x32_bf16 v[118:121], v[158:161], v[190:193], v[118:121]
	v_mfma_f32_16x16x32_bf16 v[110:113], v[150:153], v[212:215], v[110:113]
	v_mfma_f32_16x16x32_bf16 v[106:109], v[158:161], v[212:215], v[106:109]
	v_mfma_f32_16x16x32_bf16 v[98:101], v[150:153], v[220:223], v[98:101]
	v_mfma_f32_16x16x32_bf16 v[90:93], v[158:161], v[220:223], v[90:93]
	v_mfma_f32_16x16x32_bf16 v[114:117], v[162:165], v[178:181], v[114:117]
	v_mfma_f32_16x16x32_bf16 v[102:105], v[170:173], v[178:181], v[102:105]
	v_mfma_f32_16x16x32_bf16 v[94:97], v[162:165], v[186:189], v[94:97]
	v_mfma_f32_16x16x32_bf16 v[86:89], v[170:173], v[186:189], v[86:89]
	v_mfma_f32_16x16x32_bf16 v[82:85], v[162:165], v[194:197], v[82:85]
	v_mfma_f32_16x16x32_bf16 v[78:81], v[170:173], v[194:197], v[78:81]
	v_mfma_f32_16x16x32_bf16 v[74:77], v[162:165], v[216:219], v[74:77]
	v_mfma_f32_16x16x32_bf16 v[70:73], v[170:173], v[216:219], v[70:73]
	v_mfma_f32_16x16x32_bf16 v[114:117], v[166:169], v[182:185], v[114:117]
	v_mfma_f32_16x16x32_bf16 v[102:105], v[174:177], v[182:185], v[102:105]
	v_mfma_f32_16x16x32_bf16 v[94:97], v[166:169], v[190:193], v[94:97]
	v_mfma_f32_16x16x32_bf16 v[86:89], v[174:177], v[190:193], v[86:89]
	v_mfma_f32_16x16x32_bf16 v[82:85], v[166:169], v[212:215], v[82:85]
	v_mfma_f32_16x16x32_bf16 v[78:81], v[174:177], v[212:215], v[78:81]
	v_mfma_f32_16x16x32_bf16 v[74:77], v[166:169], v[220:223], v[74:77]
	v_mfma_f32_16x16x32_bf16 v[70:73], v[174:177], v[220:223], v[70:73]
	s_barrier
; #define PG8_STAGE(bufoff, gbase, voff) do { _Pragma("unroll") for (int _i = 0; _i < 2; ++_i) \
;         __builtin_amdgcn_global_load_lds((const unsigned*)((const char*)(gbase) + (voff)[_i]), (LAS unsigned*)(lds + (bufoff) + ldsw + _i * 8192), 16, 0, 0); } while (0)
; #define PG8_LDA(dst, b, h) do { _Pragma("unroll") for (int m = 0; m < 4; ++m) _Pragma("unroll") for (int k = 0; k < 2; ++k) dst[m][k] = *(const LAS bf16x8*)(lds + PG8_SA(b, h) + aoff + m * 2048 + k * 1024); } while (0)
; #define PG8_MMA(ai, bj, At, Bt) do { __builtin_amdgcn_s_setprio(1); _Pragma("unroll") for (int m = 0; m < 4; ++m) _Pragma("unroll") for (int n = 0; n < 2; ++n) _Pragma("unroll") for (int k = 0; k < 2; ++k) \
;         acc[ai][bj][m][n] = __builtin_amdgcn_mfma_f32_16x16x32_bf16(Bt[n][k], At[m][k], acc[ai][bj][m][n], 0, 0, 0); __builtin_amdgcn_s_setprio(0); } while (0)
; #define PG8_WAIT_V(n) asm volatile("s_waitcnt vmcnt(" #n ")" ::: "memory")
; #define PG8_WAIT_L(n) asm volatile("s_waitcnt lgkmcnt(" #n ")" ::: "memory")
; #define PG8_BAR __builtin_amdgcn_s_barrier()
; #define PG8_SCHED __builtin_amdgcn_sched_barrier(0)
; template <class Epi, class Sched>
; __device__ __forceinline__ void gemm_phase(LAS unsigned char* lds, const Gemm g, const Sched& S, const Epi& E) {
;     ...
;             PG8_LDA(At, 1, 1); PG8_STAGE(PG8_SB(1, 0), b3, voffB); PG8_STAGE(PG8_SB(1, 1), b3 + hstepB, voffB); PG8_STAGE(PG8_SA(1, 0), a3, voffA);
;             PG8_WAIT_V(8); PG8_WAIT_L(0); PG8_BAR; PG8_MMA(1, 0, At, B0); PG8_MMA(1, 1, At, B1); PG8_BAR; PG8_SCHED;
;         }
	s_add_i32 s28, s63, s11
	s_add_i32 m0, s28, 0xffffff80
	ds_read_b128 v[178:181], v145 offset:49152
	ds_read_b128 v[182:185], v145 offset:50176
	ds_read_b128 v[186:189], v145 offset:51200
	ds_read_b128 v[190:193], v145 offset:52224
	ds_read_b128 v[194:197], v145 offset:53248
	ds_read_b128 v[212:215], v145 offset:54272
	ds_read_b128 v[216:219], v145 offset:55296
	ds_read_b128 v[220:223], v145 offset:56320
	global_load_lds_dwordx4 v[224:225], off offset:128
	s_add_i32 m0, s28, 0x1f80
	s_add_u32 s26, s26, 0x158080
	s_addc_u32 s27, s27, 0
	s_add_i32 s28, s65, s11
	global_load_lds_dwordx4 v[226:227], off offset:128
	s_mov_b32 m0, s28
	s_nop 0
	global_load_lds_dwordx4 v4, s[26:27]
	s_add_i32 m0, s28, 0x2000
	s_nop 0
	global_load_lds_dwordx4 v2, s[26:27]
	s_add_i32 m0, s54, 0xffffff80
	s_nop 0
	global_load_lds_dwordx4 v[228:229], off offset:128
	s_add_i32 m0, s55, 0xffffff80
	s_nop 0
	global_load_lds_dwordx4 v[230:231], off offset:128
	s_waitcnt vmcnt(8)
	s_waitcnt lgkmcnt(0)
	s_barrier
	s_waitcnt lgkmcnt(0)
	v_mfma_f32_16x16x32_bf16 v[66:69], v[146:149], v[178:181], v[66:69]
	v_mfma_f32_16x16x32_bf16 v[62:65], v[154:157], v[178:181], v[62:65]
	v_mfma_f32_16x16x32_bf16 v[58:61], v[146:149], v[186:189], v[58:61]
	v_mfma_f32_16x16x32_bf16 v[54:57], v[154:157], v[186:189], v[54:57]
	v_mfma_f32_16x16x32_bf16 v[50:53], v[146:149], v[194:197], v[50:53]
	v_mfma_f32_16x16x32_bf16 v[42:45], v[154:157], v[194:197], v[42:45]
	v_mfma_f32_16x16x32_bf16 v[34:37], v[146:149], v[216:219], v[34:37]
	v_mfma_f32_16x16x32_bf16 v[26:29], v[154:157], v[216:219], v[26:29]
	v_mfma_f32_16x16x32_bf16 v[66:69], v[150:153], v[182:185], v[66:69]
	v_mfma_f32_16x16x32_bf16 v[62:65], v[158:161], v[182:185], v[62:65]
	v_mfma_f32_16x16x32_bf16 v[58:61], v[150:153], v[190:193], v[58:61]
	v_mfma_f32_16x16x32_bf16 v[54:57], v[158:161], v[190:193], v[54:57]
	v_mfma_f32_16x16x32_bf16 v[50:53], v[150:153], v[212:215], v[50:53]
	v_mfma_f32_16x16x32_bf16 v[42:45], v[158:161], v[212:215], v[42:45]
	v_mfma_f32_16x16x32_bf16 v[34:37], v[150:153], v[220:223], v[34:37]
	v_mfma_f32_16x16x32_bf16 v[26:29], v[158:161], v[220:223], v[26:29]
	v_mfma_f32_16x16x32_bf16 v[46:49], v[162:165], v[178:181], v[46:49]
	v_mfma_f32_16x16x32_bf16 v[38:41], v[170:173], v[178:181], v[38:41]
	v_mfma_f32_16x16x32_bf16 v[30:33], v[162:165], v[186:189], v[30:33]
	v_mfma_f32_16x16x32_bf16 v[22:25], v[170:173], v[186:189], v[22:25]
	v_mfma_f32_16x16x32_bf16 v[18:21], v[162:165], v[194:197], v[18:21]
	v_mfma_f32_16x16x32_bf16 v[14:17], v[170:173], v[194:197], v[14:17]
	v_mfma_f32_16x16x32_bf16 v[10:13], v[162:165], v[216:219], v[10:13]
	v_mfma_f32_16x16x32_bf16 v[6:9], v[170:173], v[216:219], v[6:9]
	v_mfma_f32_16x16x32_bf16 v[46:49], v[166:169], v[182:185], v[46:49]
	v_mfma_f32_16x16x32_bf16 v[38:41], v[174:177], v[182:185], v[38:41]
	v_mfma_f32_16x16x32_bf16 v[30:33], v[166:169], v[190:193], v[30:33]
	v_mfma_f32_16x16x32_bf16 v[22:25], v[174:177], v[190:193], v[22:25]
	v_mfma_f32_16x16x32_bf16 v[18:21], v[166:169], v[212:215], v[18:21]
	v_mfma_f32_16x16x32_bf16 v[14:17], v[174:177], v[212:215], v[14:17]
	v_mfma_f32_16x16x32_bf16 v[10:13], v[166:169], v[220:223], v[10:13]
	v_mfma_f32_16x16x32_bf16 v[6:9], v[174:177], v[220:223], v[6:9]
	s_barrier
	s_add_i32 s62, s62, 2
	s_add_u32 s24, s24, 0x100
	s_addc_u32 s25, s25, 0
	s_cmpk_gt_u32 s62, 0x53
	s_cbranch_scc0 .LBB0_281
	s_and_b64 vcc, exec, s[18:19]
	s_cbranch_vccz .LBB0_284
	s_barrier

; #define PG8_STAGE(bufoff, gbase, voff) do { _Pragma("unroll") for (int _i = 0; _i < 2; ++_i) \
;         __builtin_amdgcn_global_load_lds((const unsigned*)((const char*)(gbase) + (voff)[_i]), (LAS unsigned*)(lds + (bufoff) + ldsw + _i * 8192), 16, 0, 0); } while (0)
; #define PG8_WAIT_V(n) asm volatile("s_waitcnt vmcnt(" #n ")" ::: "memory")
; #define PG8_BAR __builtin_amdgcn_s_barrier()
;     __device__ __forceinline__ void operator()(const f32x4 (&acc)[2][2][4][2], const Unit& u, int wr, int wc, int fr, int fq) const {
;         const int row0 = u.pm * BM + wr * 64 + fr, j0 = 8 * fq, cbase = u.pn * BM + 64 * wc;
;         const f32x4 ba0 = *(const f32x4*)(bias + cbase + j0), ba1 = *(const f32x4*)(bias + cbase + j0 + 4), bb0 = *(const f32x4*)(bias + cbase + 32 + j0), bb1 = *(const f32x4*)(bias + cbase + 32 + j0 + 4);
;         const bool rot = u.pn < 9;
;         f32x4 TB[2][6];
; template <class Epi, class Sched>
; __device__ __forceinline__ void gemm_phase(LAS unsigned char* lds, const Gemm g, const Sched& S, const Epi& E) {
;     ...
;     PG8_STAGE(PG8_SB(0, 0), cB, voffB); PG8_STAGE(PG8_SB(0, 1), cB + hstepB, voffB); PG8_STAGE(PG8_SA(0, 0), cA, voffA); PG8_STAGE(PG8_SA(0, 1), cA + hstepA, voffA);
;     if (wr == 1) PG8_BAR;
;     PG8_WAIT_V(2); PG8_BAR;
;     PG8_STAGE(PG8_SB(1, 0), cB + kstep, voffB); PG8_STAGE(PG8_SA(1, 0), cA + kstep, voffA); PG8_STAGE(PG8_SB(1, 1), cB + hstepB + kstep, voffB);
;     PG8_WAIT_V(6); PG8_BAR;
.LBB0_507:
	v_lshrrev_b32_e32 v20, 1, v4
	v_and_b32_e32 v20, 24, v20
	v_and_b32_e32 v21, 15, v4
	v_lshlrev_b32_e32 v22, 1, v20
	v_lshlrev_b32_e32 v4, 2, v4
	s_and_b32 s20, s17, 3
	v_lshl_or_b32 v235, s18, 6, v21
	v_lshl_or_b32 v21, v21, 6, v22
	s_lshl_b32 s17, s18, 13
	v_and_b32_e32 v4, 32, v4
	s_add_i32 m0, s50, 0x18000
	v_lshl_add_u64 v[12:13], v[12:13], 0, s[36:37]
	v_bitop3_b32 v22, v21, s17, v4 bitop3:0xde
	s_lshl_b32 s17, s20, 12
	s_waitcnt vmcnt(2)
	s_barrier
	global_load_lds_dwordx4 v[12:13], off
	v_lshl_add_u64 v[10:11], v[10:11], 0, s[36:37]
	s_add_i32 m0, s50, 0x1a000
	s_add_i32 s54, s50, 0x8000
	s_add_i32 s55, s50, 0xa000
	global_load_lds_dwordx4 v[10:11], off
	v_lshl_add_u64 v[6:7], v[6:7], 0, s[36:37]
	s_mov_b32 m0, s54
	s_add_u32 s18, s42, 0x80080
	global_load_lds_dwordx4 v[6:7], off
	v_lshl_add_u64 v[6:7], v[8:9], 0, s[36:37]
	s_mov_b32 m0, s55
	s_addc_u32 s19, s43, 0
	global_load_lds_dwordx4 v[6:7], off
	s_add_i32 m0, s50, 0x1c000
	v_lshl_add_u64 v[6:7], s[18:19], 0, v[212:213]
	global_load_lds_dwordx4 v[6:7], off
	v_lshl_add_u64 v[6:7], s[18:19], 0, v[216:217]
	s_add_i32 m0, s50, 0x1e000
	v_bitop3_b32 v236, v21, s17, v4 bitop3:0xde
	global_load_lds_dwordx4 v[6:7], off
	v_lshlrev_b32_e32 v4, 2, v20
	v_lshl_add_u64 v[218:219], s[12:13], 0, v[4:5]
	v_lshl_add_u64 v[220:221], s[10:11], 0, v[4:5]
	v_lshl_add_u64 v[222:223], s[14:15], 0, v[4:5]
	v_lshlrev_b32_e32 v4, 15, v14
	v_and_b32_e32 v4, 0xffff0000, v4
	v_lshl_add_u32 v4, v15, 12, v4
	v_and_b32_e32 v6, 1, v14
	v_lshl_or_b32 v4, v6, 6, v4
	v_lshl_add_u32 v224, v16, 1, v4
	v_lshlrev_b32_e32 v4, 15, v17
	v_and_b32_e32 v4, 0xffff0000, v4
	s_waitcnt vmcnt(6)
	v_lshl_add_u32 v4, v18, 12, v4
	v_and_b32_e32 v6, 1, v17
	s_cmpk_lt_u32 s16, 0x100
	v_lshl_or_b32 v4, v6, 6, v4
	s_cselect_b64 s[16:17], -1, 0
	s_lshl_b32 s56, s20, 6
	v_mov_b32_e32 v225, v5
	v_lshl_add_u32 v226, v19, 1, v4
	v_mov_b32_e32 v227, v5
	s_mov_b32 s57, 0
	v_add_u32_e32 v237, 0, v22
	v_lshlrev_b32_e32 v4, 1, v20
	s_barrier
	s_branch .LBB0_510
	s_nop 0
	s_nop 0
	s_nop 0
	s_nop 0
	s_nop 0
	s_nop 0
	s_nop 0
	s_nop 0
	s_nop 0
	s_nop 0
	s_nop 0
	s_nop 0
	s_nop 0
	s_nop 0
	s_nop 0
	s_nop 0
	s_nop 0
	s_nop 0
	s_nop 0
	s_nop 0
	s_nop 0
	s_nop 0
	s_nop 0
	s_nop 0
	s_nop 0
	s_nop 0
	s_nop 0
	s_nop 0

; #define PG8_STAGE(bufoff, gbase, voff) do { _Pragma("unroll") for (int _i = 0; _i < 2; ++_i) \
;         __builtin_amdgcn_global_load_lds((const unsigned*)((const char*)(gbase) + (voff)[_i]), (LAS unsigned*)(lds + (bufoff) + ldsw + _i * 8192), 16, 0, 0); } while (0)
; #define PG8_LDA(dst, b, h) do { _Pragma("unroll") for (int m = 0; m < 4; ++m) _Pragma("unroll") for (int k = 0; k < 2; ++k) dst[m][k] = *(const LAS bf16x8*)(lds + PG8_SA(b, h) + aoff + m * 2048 + k * 1024); } while (0)
; #define PG8_LDB(dst, b, h) do { _Pragma("unroll") for (int n = 0; n < 2; ++n) _Pragma("unroll") for (int k = 0; k < 2; ++k) dst[n][k] = *(const LAS bf16x8*)(lds + PG8_SB(b, h) + boff + n * 2048 + k * 1024); } while (0)
; #define PG8_MMA(ai, bj, At, Bt) do { __builtin_amdgcn_s_setprio(1); _Pragma("unroll") for (int m = 0; m < 4; ++m) _Pragma("unroll") for (int n = 0; n < 2; ++n) _Pragma("unroll") for (int k = 0; k < 2; ++k) \
;         acc[ai][bj][m][n] = __builtin_amdgcn_mfma_f32_16x16x32_bf16(Bt[n][k], At[m][k], acc[ai][bj][m][n], 0, 0, 0); __builtin_amdgcn_s_setprio(0); } while (0)
; #define PG8_WAIT_V(n) asm volatile("s_waitcnt vmcnt(" #n ")" ::: "memory")
; #define PG8_WAIT_L(n) asm volatile("s_waitcnt lgkmcnt(" #n ")" ::: "memory")
; #define PG8_BAR __builtin_amdgcn_s_barrier()
; #define PG8_SCHED __builtin_amdgcn_sched_barrier(0)
; template <class Epi, class Sched>
; __device__ __forceinline__ void gemm_phase(LAS unsigned char* lds, const Gemm g, const Sched& S, const Epi& E) {
;     ...
;             const bool last = (t == nt - 2);
;             const char* a1 = cA + (size_t)(t + 1) * kstep;
;             const char* a2 = last ? nA : cA + (size_t)(t + 2) * kstep; const char* b2 = last ? nB : cB + (size_t)(t + 2) * kstep;
;             const char* a3 = a2 + kstep; const char* b3 = b2 + kstep;
;             if (last && has_next) S.a_ready(nxt);
;             PG8_LDB(B0, 0, 0); PG8_LDB(B1, 0, 1); PG8_SCHED; PG8_LDA(At, 0, 0); PG8_STAGE(PG8_SA(1, 1), a1 + hstepA, voffA);
;             PG8_WAIT_V(8); PG8_WAIT_L(0); PG8_BAR; PG8_MMA(0, 0, At, B0); PG8_MMA(0, 1, At, B1); PG8_BAR; PG8_SCHED;
;             PG8_LDA(At, 0, 1); PG8_STAGE(PG8_SB(0, 0), b2, voffB); PG8_STAGE(PG8_SB(0, 1), b2 + hstepB, voffB); PG8_STAGE(PG8_SA(0, 0), a2, voffA);
.LBB0_513:
	s_add_u32 s42, s38, 0xfff80080
	s_addc_u32 s43, s39, -1
	s_add_i32 s61, 0, 0x10000
	s_cmp_eq_u32 s60, 28
	s_cselect_b32 s45, s21, s43
	s_cselect_b32 s44, s27, s42
	s_cselect_b32 s43, s19, s59
	s_cselect_b32 s42, s29, s58
	s_add_i32 s64, 0, 0x14000
	v_add_u32_e32 v98, s61, v236
	v_add_u32_e32 v162, s64, v236
	ds_read_b128 v[86:89], v98
	ds_read_b128 v[90:93], v98 offset:1024
	ds_read_b128 v[94:97], v98 offset:2048
	ds_read_b128 v[98:101], v98 offset:3072
	ds_read_b128 v[150:153], v162
	ds_read_b128 v[154:157], v162 offset:1024
	ds_read_b128 v[158:161], v162 offset:2048
	ds_read_b128 v[162:165], v162 offset:3072
	s_add_i32 m0, s50, 0xc000
	ds_read_b128 v[166:169], v237
	ds_read_b128 v[170:173], v237 offset:1024
	ds_read_b128 v[174:177], v237 offset:2048
	ds_read_b128 v[178:181], v237 offset:3072
	ds_read_b128 v[182:185], v237 offset:4096
	ds_read_b128 v[186:189], v237 offset:5120
	ds_read_b128 v[190:193], v237 offset:6144
	ds_read_b128 v[194:197], v237 offset:7168
	global_load_lds_dwordx4 v224, s[38:39]
	s_add_i32 m0, s50, 0xe000
	s_nop 0
	global_load_lds_dwordx4 v226, s[38:39]
	s_waitcnt vmcnt(8)
	s_waitcnt lgkmcnt(0)
	s_barrier
	s_waitcnt lgkmcnt(0)
	v_mfma_f32_16x16x32_bf16 v[146:149], v[86:89], v[166:169], v[146:149]
	v_mfma_f32_16x16x32_bf16 v[142:145], v[94:97], v[166:169], v[142:145]
	v_mfma_f32_16x16x32_bf16 v[130:133], v[86:89], v[174:177], v[130:133]
	v_mfma_f32_16x16x32_bf16 v[126:129], v[94:97], v[174:177], v[126:129]
	v_mfma_f32_16x16x32_bf16 v[114:117], v[86:89], v[182:185], v[114:117]
	v_mfma_f32_16x16x32_bf16 v[110:113], v[94:97], v[182:185], v[110:113]
	v_mfma_f32_16x16x32_bf16 v[82:85], v[86:89], v[190:193], v[82:85]
	v_mfma_f32_16x16x32_bf16 v[78:81], v[94:97], v[190:193], v[78:81]
	v_mfma_f32_16x16x32_bf16 v[146:149], v[90:93], v[170:173], v[146:149]
	v_mfma_f32_16x16x32_bf16 v[142:145], v[98:101], v[170:173], v[142:145]
	v_mfma_f32_16x16x32_bf16 v[130:133], v[90:93], v[178:181], v[130:133]
	v_mfma_f32_16x16x32_bf16 v[126:129], v[98:101], v[178:181], v[126:129]
	v_mfma_f32_16x16x32_bf16 v[114:117], v[90:93], v[186:189], v[114:117]
	v_mfma_f32_16x16x32_bf16 v[110:113], v[98:101], v[186:189], v[110:113]
	v_mfma_f32_16x16x32_bf16 v[82:85], v[90:93], v[194:197], v[82:85]
	v_mfma_f32_16x16x32_bf16 v[78:81], v[98:101], v[194:197], v[78:81]
	v_mfma_f32_16x16x32_bf16 v[138:141], v[150:153], v[166:169], v[138:141]
	v_mfma_f32_16x16x32_bf16 v[134:137], v[158:161], v[166:169], v[134:137]
	v_mfma_f32_16x16x32_bf16 v[122:125], v[150:153], v[174:177], v[122:125]
	v_mfma_f32_16x16x32_bf16 v[118:121], v[158:161], v[174:177], v[118:121]
	v_mfma_f32_16x16x32_bf16 v[106:109], v[150:153], v[182:185], v[106:109]
	v_mfma_f32_16x16x32_bf16 v[102:105], v[158:161], v[182:185], v[102:105]
	v_mfma_f32_16x16x32_bf16 v[74:77], v[150:153], v[190:193], v[74:77]
	v_mfma_f32_16x16x32_bf16 v[70:73], v[158:161], v[190:193], v[70:73]
	v_mfma_f32_16x16x32_bf16 v[138:141], v[154:157], v[170:173], v[138:141]
	v_mfma_f32_16x16x32_bf16 v[134:137], v[162:165], v[170:173], v[134:137]
	v_mfma_f32_16x16x32_bf16 v[122:125], v[154:157], v[178:181], v[122:125]
	v_mfma_f32_16x16x32_bf16 v[118:121], v[162:165], v[178:181], v[118:121]
	v_mfma_f32_16x16x32_bf16 v[106:109], v[154:157], v[186:189], v[106:109]
	v_mfma_f32_16x16x32_bf16 v[102:105], v[162:165], v[186:189], v[102:105]
	v_mfma_f32_16x16x32_bf16 v[74:77], v[154:157], v[194:197], v[74:77]
	v_mfma_f32_16x16x32_bf16 v[70:73], v[162:165], v[194:197], v[70:73]
	s_barrier
	s_add_i32 s61, s61, s49
	v_lshl_add_u64 v[228:229], s[42:43], 0, v[212:213]
	s_mov_b32 m0, s61
	ds_read_b128 v[166:169], v237 offset:16384
	ds_read_b128 v[170:173], v237 offset:17408
	ds_read_b128 v[174:177], v237 offset:18432
	ds_read_b128 v[178:181], v237 offset:19456
	ds_read_b128 v[182:185], v237 offset:20480
	ds_read_b128 v[186:189], v237 offset:21504
	ds_read_b128 v[190:193], v237 offset:22528
	ds_read_b128 v[194:197], v237 offset:23552
	global_load_lds_dwordx4 v[228:229], off
	s_add_i32 m0, s61, 0x2000
	s_add_u32 s62, s42, 0x80000
	v_lshl_add_u64 v[230:231], s[42:43], 0, v[216:217]
	s_addc_u32 s63, s43, 0
	s_add_i32 s61, s64, s49
	global_load_lds_dwordx4 v[230:231], off
	s_mov_b32 m0, s61
	v_lshl_add_u64 v[240:241], s[44:45], 0, v[214:215]
	global_load_lds_dwordx4 v212, s[62:63]
	s_add_i32 m0, s61, 0x2000
	s_nop 0
	global_load_lds_dwordx4 v216, s[62:63]
	v_lshl_add_u64 v[238:239], s[44:45], 0, v[2:3]
	s_mov_b32 m0, s50
	s_nop 0
	global_load_lds_dwordx4 v[238:239], off
	s_mov_b32 m0, s51
	s_nop 0
	global_load_lds_dwordx4 v[240:241], off
	s_waitcnt vmcnt(8)
	s_waitcnt lgkmcnt(0)
	s_barrier
; #define PG8_STAGE(bufoff, gbase, voff) do { _Pragma("unroll") for (int _i = 0; _i < 2; ++_i) \
;         __builtin_amdgcn_global_load_lds((const unsigned*)((const char*)(gbase) + (voff)[_i]), (LAS unsigned*)(lds + (bufoff) + ldsw + _i * 8192), 16, 0, 0); } while (0)
; #define PG8_LDA(dst, b, h) do { _Pragma("unroll") for (int m = 0; m < 4; ++m) _Pragma("unroll") for (int k = 0; k < 2; ++k) dst[m][k] = *(const LAS bf16x8*)(lds + PG8_SA(b, h) + aoff + m * 2048 + k * 1024); } while (0)
; #define PG8_LDB(dst, b, h) do { _Pragma("unroll") for (int n = 0; n < 2; ++n) _Pragma("unroll") for (int k = 0; k < 2; ++k) dst[n][k] = *(const LAS bf16x8*)(lds + PG8_SB(b, h) + boff + n * 2048 + k * 1024); } while (0)
; #define PG8_MMA(ai, bj, At, Bt) do { __builtin_amdgcn_s_setprio(1); _Pragma("unroll") for (int m = 0; m < 4; ++m) _Pragma("unroll") for (int n = 0; n < 2; ++n) _Pragma("unroll") for (int k = 0; k < 2; ++k) \
;         acc[ai][bj][m][n] = __builtin_amdgcn_mfma_f32_16x16x32_bf16(Bt[n][k], At[m][k], acc[ai][bj][m][n], 0, 0, 0); __builtin_amdgcn_s_setprio(0); } while (0)
; #define PG8_WAIT_V(n) asm volatile("s_waitcnt vmcnt(" #n ")" ::: "memory")
; #define PG8_WAIT_L(n) asm volatile("s_waitcnt lgkmcnt(" #n ")" ::: "memory")
; #define PG8_BAR __builtin_amdgcn_s_barrier()
; #define PG8_SCHED __builtin_amdgcn_sched_barrier(0)
; template <class Epi, class Sched>
; __device__ __forceinline__ void gemm_phase(LAS unsigned char* lds, const Gemm g, const Sched& S, const Epi& E) {
;     ...
;             PG8_WAIT_V(8); PG8_WAIT_L(0); PG8_BAR; PG8_MMA(1, 0, At, B0); PG8_MMA(1, 1, At, B1); PG8_BAR; PG8_SCHED;
;             PG8_LDB(B0, 1, 0); PG8_LDB(B1, 1, 1); PG8_SCHED; PG8_LDA(At, 1, 0); PG8_STAGE(PG8_SA(0, 1), a2 + hstepA, voffA);
;             PG8_WAIT_V(8); PG8_WAIT_L(0); PG8_BAR; PG8_MMA(0, 0, At, B0); PG8_MMA(0, 1, At, B1); PG8_BAR; PG8_SCHED;
	s_waitcnt lgkmcnt(0)
	v_mfma_f32_16x16x32_bf16 v[66:69], v[86:89], v[166:169], v[66:69]
	v_mfma_f32_16x16x32_bf16 v[62:65], v[94:97], v[166:169], v[62:65]
	v_mfma_f32_16x16x32_bf16 v[50:53], v[86:89], v[174:177], v[50:53]
	v_mfma_f32_16x16x32_bf16 v[46:49], v[94:97], v[174:177], v[46:49]
	v_mfma_f32_16x16x32_bf16 v[34:37], v[86:89], v[182:185], v[34:37]
	v_mfma_f32_16x16x32_bf16 v[30:33], v[94:97], v[182:185], v[30:33]
	v_mfma_f32_16x16x32_bf16 v[18:21], v[86:89], v[190:193], v[18:21]
	v_mfma_f32_16x16x32_bf16 v[14:17], v[94:97], v[190:193], v[14:17]
	v_mfma_f32_16x16x32_bf16 v[66:69], v[90:93], v[170:173], v[66:69]
	v_mfma_f32_16x16x32_bf16 v[62:65], v[98:101], v[170:173], v[62:65]
	v_mfma_f32_16x16x32_bf16 v[50:53], v[90:93], v[178:181], v[50:53]
	v_mfma_f32_16x16x32_bf16 v[46:49], v[98:101], v[178:181], v[46:49]
	v_mfma_f32_16x16x32_bf16 v[34:37], v[90:93], v[186:189], v[34:37]
	v_mfma_f32_16x16x32_bf16 v[30:33], v[98:101], v[186:189], v[30:33]
	v_mfma_f32_16x16x32_bf16 v[18:21], v[90:93], v[194:197], v[18:21]
	v_mfma_f32_16x16x32_bf16 v[14:17], v[98:101], v[194:197], v[14:17]
	v_mfma_f32_16x16x32_bf16 v[58:61], v[150:153], v[166:169], v[58:61]
	v_mfma_f32_16x16x32_bf16 v[54:57], v[158:161], v[166:169], v[54:57]
	v_mfma_f32_16x16x32_bf16 v[42:45], v[150:153], v[174:177], v[42:45]
	v_mfma_f32_16x16x32_bf16 v[38:41], v[158:161], v[174:177], v[38:41]
	v_mfma_f32_16x16x32_bf16 v[26:29], v[150:153], v[182:185], v[26:29]
	v_mfma_f32_16x16x32_bf16 v[22:25], v[158:161], v[182:185], v[22:25]
	v_mfma_f32_16x16x32_bf16 v[10:13], v[150:153], v[190:193], v[10:13]
	v_mfma_f32_16x16x32_bf16 v[6:9], v[158:161], v[190:193], v[6:9]
	v_mfma_f32_16x16x32_bf16 v[58:61], v[154:157], v[170:173], v[58:61]
	v_mfma_f32_16x16x32_bf16 v[54:57], v[162:165], v[170:173], v[54:57]
	v_mfma_f32_16x16x32_bf16 v[42:45], v[154:157], v[178:181], v[42:45]
	v_mfma_f32_16x16x32_bf16 v[38:41], v[162:165], v[178:181], v[38:41]
	v_mfma_f32_16x16x32_bf16 v[26:29], v[154:157], v[186:189], v[26:29]
	v_mfma_f32_16x16x32_bf16 v[22:25], v[162:165], v[186:189], v[22:25]
	v_mfma_f32_16x16x32_bf16 v[10:13], v[154:157], v[194:197], v[10:13]
	v_mfma_f32_16x16x32_bf16 v[6:9], v[162:165], v[194:197], v[6:9]
	s_barrier
	s_add_i32 s61, 0, 0x18000
	s_add_i32 s62, 0, 0x1c000
	v_add_u32_e32 v98, s61, v236
	v_add_u32_e32 v162, s62, v236
	ds_read_b128 v[86:89], v98
	ds_read_b128 v[90:93], v98 offset:1024
	ds_read_b128 v[94:97], v98 offset:2048
	ds_read_b128 v[98:101], v98 offset:3072
	ds_read_b128 v[150:153], v162
	ds_read_b128 v[154:157], v162 offset:1024
	ds_read_b128 v[158:161], v162 offset:2048
	ds_read_b128 v[162:165], v162 offset:3072
	s_add_u32 s44, s44, 0x80000
	s_addc_u32 s45, s45, 0
	s_mov_b32 m0, s52
	ds_read_b128 v[166:169], v237 offset:32768
	ds_read_b128 v[170:173], v237 offset:33792
	ds_read_b128 v[174:177], v237 offset:34816
	ds_read_b128 v[178:181], v237 offset:35840
	ds_read_b128 v[182:185], v237 offset:36864
	ds_read_b128 v[186:189], v237 offset:37888
	ds_read_b128 v[190:193], v237 offset:38912
	ds_read_b128 v[194:197], v237 offset:39936
	global_load_lds_dwordx4 v2, s[44:45]
	s_mov_b32 m0, s53
	s_nop 0
	global_load_lds_dwordx4 v214, s[44:45]
	s_waitcnt vmcnt(8)
	s_waitcnt lgkmcnt(0)
	s_barrier
	s_waitcnt lgkmcnt(0)
	v_mfma_f32_16x16x32_bf16 v[146:149], v[86:89], v[166:169], v[146:149]
	v_mfma_f32_16x16x32_bf16 v[142:145], v[94:97], v[166:169], v[142:145]
	v_mfma_f32_16x16x32_bf16 v[130:133], v[86:89], v[174:177], v[130:133]
	v_mfma_f32_16x16x32_bf16 v[126:129], v[94:97], v[174:177], v[126:129]
	v_mfma_f32_16x16x32_bf16 v[114:117], v[86:89], v[182:185], v[114:117]
	v_mfma_f32_16x16x32_bf16 v[110:113], v[94:97], v[182:185], v[110:113]
	v_mfma_f32_16x16x32_bf16 v[82:85], v[86:89], v[190:193], v[82:85]
	v_mfma_f32_16x16x32_bf16 v[78:81], v[94:97], v[190:193], v[78:81]
	v_mfma_f32_16x16x32_bf16 v[146:149], v[90:93], v[170:173], v[146:149]
	v_mfma_f32_16x16x32_bf16 v[142:145], v[98:101], v[170:173], v[142:145]
	v_mfma_f32_16x16x32_bf16 v[130:133], v[90:93], v[178:181], v[130:133]
	v_mfma_f32_16x16x32_bf16 v[126:129], v[98:101], v[178:181], v[126:129]
	v_mfma_f32_16x16x32_bf16 v[114:117], v[90:93], v[186:189], v[114:117]
	v_mfma_f32_16x16x32_bf16 v[110:113], v[98:101], v[186:189], v[110:113]
	v_mfma_f32_16x16x32_bf16 v[82:85], v[90:93], v[194:197], v[82:85]
	v_mfma_f32_16x16x32_bf16 v[78:81], v[98:101], v[194:197], v[78:81]
	v_mfma_f32_16x16x32_bf16 v[138:141], v[150:153], v[166:169], v[138:141]
	v_mfma_f32_16x16x32_bf16 v[134:137], v[158:161], v[166:169], v[134:137]
	v_mfma_f32_16x16x32_bf16 v[122:125], v[150:153], v[174:177], v[122:125]
	v_mfma_f32_16x16x32_bf16 v[118:121], v[158:161], v[174:177], v[118:121]
	v_mfma_f32_16x16x32_bf16 v[106:109], v[150:153], v[182:185], v[106:109]
	v_mfma_f32_16x16x32_bf16 v[102:105], v[158:161], v[182:185], v[102:105]
	v_mfma_f32_16x16x32_bf16 v[74:77], v[150:153], v[190:193], v[74:77]
	v_mfma_f32_16x16x32_bf16 v[70:73], v[158:161], v[190:193], v[70:73]
	v_mfma_f32_16x16x32_bf16 v[138:141], v[154:157], v[170:173], v[138:141]
	v_mfma_f32_16x16x32_bf16 v[134:137], v[162:165], v[170:173], v[134:137]
	v_mfma_f32_16x16x32_bf16 v[122:125], v[154:157], v[178:181], v[122:125]
	v_mfma_f32_16x16x32_bf16 v[118:121], v[162:165], v[178:181], v[118:121]
	v_mfma_f32_16x16x32_bf16 v[106:109], v[154:157], v[186:189], v[106:109]
	v_mfma_f32_16x16x32_bf16 v[102:105], v[162:165], v[186:189], v[102:105]
	v_mfma_f32_16x16x32_bf16 v[74:77], v[154:157], v[194:197], v[74:77]
	v_mfma_f32_16x16x32_bf16 v[70:73], v[162:165], v[194:197], v[70:73]
	s_barrier
; #define PG8_STAGE(bufoff, gbase, voff) do { _Pragma("unroll") for (int _i = 0; _i < 2; ++_i) \
;         __builtin_amdgcn_global_load_lds((const unsigned*)((const char*)(gbase) + (voff)[_i]), (LAS unsigned*)(lds + (bufoff) + ldsw + _i * 8192), 16, 0, 0); } while (0)
; #define PG8_LDA(dst, b, h) do { _Pragma("unroll") for (int m = 0; m < 4; ++m) _Pragma("unroll") for (int k = 0; k < 2; ++k) dst[m][k] = *(const LAS bf16x8*)(lds + PG8_SA(b, h) + aoff + m * 2048 + k * 1024); } while (0)
; #define PG8_MMA(ai, bj, At, Bt) do { __builtin_amdgcn_s_setprio(1); _Pragma("unroll") for (int m = 0; m < 4; ++m) _Pragma("unroll") for (int n = 0; n < 2; ++n) _Pragma("unroll") for (int k = 0; k < 2; ++k) \
;         acc[ai][bj][m][n] = __builtin_amdgcn_mfma_f32_16x16x32_bf16(Bt[n][k], At[m][k], acc[ai][bj][m][n], 0, 0, 0); __builtin_amdgcn_s_setprio(0); } while (0)
; #define PG8_WAIT_V(n) asm volatile("s_waitcnt vmcnt(" #n ")" ::: "memory")
; #define PG8_WAIT_L(n) asm volatile("s_waitcnt lgkmcnt(" #n ")" ::: "memory")
; #define PG8_BAR __builtin_amdgcn_s_barrier()
; #define PG8_SCHED __builtin_amdgcn_sched_barrier(0)
; template <class Epi, class Sched>
; __device__ __forceinline__ void gemm_phase(LAS unsigned char* lds, const Gemm g, const Sched& S, const Epi& E) {
;     ...
;             PG8_LDA(At, 1, 1); PG8_STAGE(PG8_SB(1, 0), b3, voffB); PG8_STAGE(PG8_SB(1, 1), b3 + hstepB, voffB); PG8_STAGE(PG8_SA(1, 0), a3, voffA);
;             PG8_WAIT_V(8); PG8_WAIT_L(0); PG8_BAR; PG8_MMA(1, 0, At, B0); PG8_MMA(1, 1, At, B1); PG8_BAR; PG8_SCHED;
;         }
	s_add_i32 s44, s61, s49
	s_add_i32 m0, s44, 0xffffff80
	ds_read_b128 v[166:169], v237 offset:49152
	ds_read_b128 v[170:173], v237 offset:50176
	ds_read_b128 v[174:177], v237 offset:51200
	ds_read_b128 v[178:181], v237 offset:52224
	ds_read_b128 v[182:185], v237 offset:53248
	ds_read_b128 v[186:189], v237 offset:54272
	ds_read_b128 v[190:193], v237 offset:55296
	ds_read_b128 v[194:197], v237 offset:56320
	global_load_lds_dwordx4 v[228:229], off offset:128
	s_add_i32 m0, s44, 0x1f80
	s_add_u32 s42, s42, 0x80080
	s_addc_u32 s43, s43, 0
	s_add_i32 s44, s62, s49
	global_load_lds_dwordx4 v[230:231], off offset:128
	s_mov_b32 m0, s44
	s_nop 0
	global_load_lds_dwordx4 v212, s[42:43]
	s_add_i32 m0, s44, 0x2000
	s_nop 0
	global_load_lds_dwordx4 v216, s[42:43]
	s_add_i32 m0, s54, 0xffffff80
	s_nop 0
	global_load_lds_dwordx4 v[238:239], off offset:128
	s_add_i32 m0, s55, 0xffffff80
	s_nop 0
	global_load_lds_dwordx4 v[240:241], off offset:128
	s_waitcnt vmcnt(8)
	s_waitcnt lgkmcnt(0)
	s_barrier
	s_waitcnt lgkmcnt(0)
	v_mfma_f32_16x16x32_bf16 v[66:69], v[86:89], v[166:169], v[66:69]
	v_mfma_f32_16x16x32_bf16 v[62:65], v[94:97], v[166:169], v[62:65]
	v_mfma_f32_16x16x32_bf16 v[50:53], v[86:89], v[174:177], v[50:53]
	v_mfma_f32_16x16x32_bf16 v[46:49], v[94:97], v[174:177], v[46:49]
	v_mfma_f32_16x16x32_bf16 v[34:37], v[86:89], v[182:185], v[34:37]
	v_mfma_f32_16x16x32_bf16 v[30:33], v[94:97], v[182:185], v[30:33]
	v_mfma_f32_16x16x32_bf16 v[18:21], v[86:89], v[190:193], v[18:21]
	v_mfma_f32_16x16x32_bf16 v[14:17], v[94:97], v[190:193], v[14:17]
	v_mfma_f32_16x16x32_bf16 v[66:69], v[90:93], v[170:173], v[66:69]
	v_mfma_f32_16x16x32_bf16 v[62:65], v[98:101], v[170:173], v[62:65]
	v_mfma_f32_16x16x32_bf16 v[50:53], v[90:93], v[178:181], v[50:53]
	v_mfma_f32_16x16x32_bf16 v[46:49], v[98:101], v[178:181], v[46:49]
	v_mfma_f32_16x16x32_bf16 v[34:37], v[90:93], v[186:189], v[34:37]
	v_mfma_f32_16x16x32_bf16 v[30:33], v[98:101], v[186:189], v[30:33]
	v_mfma_f32_16x16x32_bf16 v[18:21], v[90:93], v[194:197], v[18:21]
	v_mfma_f32_16x16x32_bf16 v[14:17], v[98:101], v[194:197], v[14:17]
	v_mfma_f32_16x16x32_bf16 v[58:61], v[150:153], v[166:169], v[58:61]
	v_mfma_f32_16x16x32_bf16 v[54:57], v[158:161], v[166:169], v[54:57]
	v_mfma_f32_16x16x32_bf16 v[42:45], v[150:153], v[174:177], v[42:45]
	v_mfma_f32_16x16x32_bf16 v[38:41], v[158:161], v[174:177], v[38:41]
	v_mfma_f32_16x16x32_bf16 v[26:29], v[150:153], v[182:185], v[26:29]
	v_mfma_f32_16x16x32_bf16 v[22:25], v[158:161], v[182:185], v[22:25]
	v_mfma_f32_16x16x32_bf16 v[10:13], v[150:153], v[190:193], v[10:13]
	v_mfma_f32_16x16x32_bf16 v[6:9], v[158:161], v[190:193], v[6:9]
	v_mfma_f32_16x16x32_bf16 v[58:61], v[154:157], v[170:173], v[58:61]
	v_mfma_f32_16x16x32_bf16 v[54:57], v[162:165], v[170:173], v[54:57]
	v_mfma_f32_16x16x32_bf16 v[42:45], v[154:157], v[178:181], v[42:45]
	v_mfma_f32_16x16x32_bf16 v[38:41], v[162:165], v[178:181], v[38:41]
	v_mfma_f32_16x16x32_bf16 v[26:29], v[154:157], v[186:189], v[26:29]
	v_mfma_f32_16x16x32_bf16 v[22:25], v[162:165], v[186:189], v[22:25]
	v_mfma_f32_16x16x32_bf16 v[10:13], v[154:157], v[194:197], v[10:13]
	v_mfma_f32_16x16x32_bf16 v[6:9], v[162:165], v[194:197], v[6:9]
	s_barrier
	s_add_i32 s60, s60, 2
	s_add_u32 s38, s38, 0x100
	s_addc_u32 s39, s39, 0
	s_add_u32 s58, s58, 0x100
	s_addc_u32 s59, s59, 0
	s_cmp_gt_u32 s60, 29
	s_cbranch_scc0 .LBB0_513
	s_and_b64 vcc, exec, s[16:17]
	s_cbranch_vccz .LBB0_516
	s_barrier

; __device__ __forceinline__ float log2_gamma(int hd) { const float e = ldexpf(1.0f, -5 - hd); float p = 1.0f / 7.0f; p = p * e + 1.0f / 6.0f; p = p * e + 0.2f; p = p * e + 0.25f; p = p * e + 1.0f / 3.0f; p = p * e + 0.5f; p = p * e + 1.0f; return -1.44269504089f * e * p; }
; #define PG8_STAGE(bufoff, gbase, voff) do { _Pragma("unroll") for (int _i = 0; _i < 2; ++_i) \
;         __builtin_amdgcn_global_load_lds((const unsigned*)((const char*)(gbase) + (voff)[_i]), (LAS unsigned*)(lds + (bufoff) + ldsw + _i * 8192), 16, 0, 0); } while (0)
; #define PG8_WAIT_V(n) asm volatile("s_waitcnt vmcnt(" #n ")" ::: "memory")
; #define PG8_BAR __builtin_amdgcn_s_barrier()
;     __device__ __forceinline__ void operator()(const f32x4 (&acc)[2][2][4][2], const Unit& u, int wr, int wc, int fr, int fq) const {
;         const int row0 = u.pm * BM + wr * 64 + fr, j0 = wc * 32 + 8 * fq;
;         if (u.pn < 16) {
;             const int hd = u.pn & 7; const bool isq = u.pn < 8;
;             const float l2g = log2_gamma(hd);
;             f32x4 TB[2][6];
; template <class Epi, class Sched>
; __device__ __forceinline__ void gemm_phase(LAS unsigned char* lds, const Gemm g, const Sched& S, const Epi& E) {
;     ...
;     PG8_STAGE(PG8_SB(0, 0), cB, voffB); PG8_STAGE(PG8_SB(0, 1), cB + hstepB, voffB); PG8_STAGE(PG8_SA(0, 0), cA, voffA); PG8_STAGE(PG8_SA(0, 1), cA + hstepA, voffA);
;     if (wr == 1) PG8_BAR;
;     PG8_WAIT_V(2); PG8_BAR;
;     PG8_STAGE(PG8_SB(1, 0), cB + kstep, voffB); PG8_STAGE(PG8_SA(1, 0), cA + kstep, voffA); PG8_STAGE(PG8_SB(1, 1), cB + hstepB + kstep, voffB);
;     PG8_WAIT_V(6); PG8_BAR;
.LBB0_649:
	s_add_u32 s8, s14, 0xd000000
	v_lshrrev_b32_e32 v20, 1, v4
	s_addc_u32 s9, s15, 0
	v_and_b32_e32 v189, 15, v4
	v_and_b32_e32 v21, 24, v20
	s_add_u32 s10, s14, 0x100000
	v_lshlrev_b32_e32 v20, 1, v21
	v_lshlrev_b32_e32 v22, 6, v189
	v_lshlrev_b32_e32 v4, 2, v4
	s_addc_u32 s11, s15, 0
	s_and_b32 s18, s13, 3
	v_or_b32_e32 v23, v22, v20
	s_lshl_b32 s13, s16, 13
	v_and_b32_e32 v4, 32, v4
	s_add_i32 m0, s47, 0x18000
	v_lshl_add_u64 v[12:13], v[12:13], 0, s[36:37]
	s_lshl_b32 s51, s16, 6
	v_bitop3_b32 v24, v23, s13, v4 bitop3:0xde
	s_lshl_b32 s13, s18, 12
	s_waitcnt vmcnt(2)
	s_barrier
	global_load_lds_dwordx4 v[12:13], off
	v_lshl_add_u64 v[10:11], v[10:11], 0, s[36:37]
	s_add_i32 m0, s47, 0x1a000
	s_add_i32 s52, s47, 0x8000
	s_add_i32 s53, s47, 0xa000
	global_load_lds_dwordx4 v[10:11], off
	v_lshl_add_u64 v[6:7], v[6:7], 0, s[36:37]
	s_mov_b32 m0, s52
	s_add_u32 s16, s28, 0x80080
	global_load_lds_dwordx4 v[6:7], off
	v_lshl_add_u64 v[6:7], v[8:9], 0, s[36:37]
	s_mov_b32 m0, s53
	s_addc_u32 s17, s29, 0
	global_load_lds_dwordx4 v[6:7], off
	s_add_i32 m0, s47, 0x1c000
	v_lshl_add_u64 v[6:7], s[16:17], 0, v[182:183]
	global_load_lds_dwordx4 v[6:7], off
	v_lshl_add_u64 v[6:7], s[16:17], 0, v[186:187]
	s_add_i32 m0, s47, 0x1e000
	v_lshl_or_b32 v188, s18, 5, v21
	global_load_lds_dwordx4 v[6:7], off
	v_bitop3_b32 v231, v23, s13, v4 bitop3:0xde
	v_lshlrev_b32_e32 v4, 2, v188
	v_lshl_add_u64 v[6:7], s[14:15], 0, v[4:5]
	s_mov_b64 s[16:17], 0x200000
	s_cmpk_lt_u32 s12, 0x100
	v_lshl_add_u64 v[190:191], v[6:7], 0, s[16:17]
	s_mov_b64 s[16:17], 0x600000
	s_cselect_b64 s[12:13], -1, 0
	v_lshl_add_u64 v[192:193], v[6:7], 0, s[16:17]
	s_lshl_b32 s16, s18, 10
	s_add_u32 s14, s14, s16
	s_addc_u32 s15, s15, 0
	v_mov_b32_e32 v23, v5
	v_lshl_add_u64 v[6:7], s[14:15], 0, v[22:23]
	v_mov_b32_e32 v21, v5
	v_lshlrev_b32_e32 v4, 15, v14
	v_lshl_add_u64 v[6:7], v[6:7], 0, v[20:21]
	s_mov_b64 s[14:15], 0x5000000
	v_and_b32_e32 v4, 0xffff0000, v4
	v_lshl_add_u64 v[194:195], v[6:7], 0, s[14:15]
	v_lshl_add_u32 v4, v15, 12, v4
	v_and_b32_e32 v6, 1, v14
	v_lshl_or_b32 v4, v6, 6, v4
	v_lshl_add_u32 v196, v16, 1, v4
	v_lshlrev_b32_e32 v4, 15, v17
	v_and_b32_e32 v4, 0xffff0000, v4
	s_waitcnt vmcnt(6)
	v_lshl_add_u32 v4, v18, 12, v4
	v_and_b32_e32 v6, 1, v17
	v_lshl_or_b32 v4, v6, 6, v4
	v_mov_b32_e32 v197, v5
	v_lshl_add_u32 v212, v19, 1, v4
	v_mov_b32_e32 v213, v5
	s_mov_b32 s54, 0
	v_add_u32_e32 v235, 0, v24
	s_barrier
	s_branch .LBB0_652
	s_nop 0
	s_nop 0
	s_nop 0
	s_nop 0
	s_nop 0
	s_nop 0
	s_nop 0
	s_nop 0
	s_nop 0
	s_nop 0
	s_nop 0
	s_nop 0
	s_nop 0
	s_nop 0
	s_nop 0
	s_nop 0
	s_nop 0
	s_nop 0
	s_nop 0
	s_nop 0
	s_nop 0
	s_nop 0
	s_nop 0
	s_nop 0
	s_nop 0

; #define PG8_STAGE(bufoff, gbase, voff) do { _Pragma("unroll") for (int _i = 0; _i < 2; ++_i) \
;         __builtin_amdgcn_global_load_lds((const unsigned*)((const char*)(gbase) + (voff)[_i]), (LAS unsigned*)(lds + (bufoff) + ldsw + _i * 8192), 16, 0, 0); } while (0)
; #define PG8_LDA(dst, b, h) do { _Pragma("unroll") for (int m = 0; m < 4; ++m) _Pragma("unroll") for (int k = 0; k < 2; ++k) dst[m][k] = *(const LAS bf16x8*)(lds + PG8_SA(b, h) + aoff + m * 2048 + k * 1024); } while (0)
; #define PG8_LDB(dst, b, h) do { _Pragma("unroll") for (int n = 0; n < 2; ++n) _Pragma("unroll") for (int k = 0; k < 2; ++k) dst[n][k] = *(const LAS bf16x8*)(lds + PG8_SB(b, h) + boff + n * 2048 + k * 1024); } while (0)
; #define PG8_MMA(ai, bj, At, Bt) do { __builtin_amdgcn_s_setprio(1); _Pragma("unroll") for (int m = 0; m < 4; ++m) _Pragma("unroll") for (int n = 0; n < 2; ++n) _Pragma("unroll") for (int k = 0; k < 2; ++k) \
;         acc[ai][bj][m][n] = __builtin_amdgcn_mfma_f32_16x16x32_bf16(Bt[n][k], At[m][k], acc[ai][bj][m][n], 0, 0, 0); __builtin_amdgcn_s_setprio(0); } while (0)
; #define PG8_WAIT_V(n) asm volatile("s_waitcnt vmcnt(" #n ")" ::: "memory")
; #define PG8_WAIT_L(n) asm volatile("s_waitcnt lgkmcnt(" #n ")" ::: "memory")
; #define PG8_BAR __builtin_amdgcn_s_barrier()
; #define PG8_SCHED __builtin_amdgcn_sched_barrier(0)
; template <class Epi, class Sched>
; __device__ __forceinline__ void gemm_phase(LAS unsigned char* lds, const Gemm g, const Sched& S, const Epi& E) {
;     ...
;             const bool last = (t == nt - 2);
;             const char* a1 = cA + (size_t)(t + 1) * kstep;
;             const char* a2 = last ? nA : cA + (size_t)(t + 2) * kstep; const char* b2 = last ? nB : cB + (size_t)(t + 2) * kstep;
;             const char* a3 = a2 + kstep; const char* b3 = b2 + kstep;
;             if (last && has_next) S.a_ready(nxt);
;             PG8_LDB(B0, 0, 0); PG8_LDB(B1, 0, 1); PG8_SCHED; PG8_LDA(At, 0, 0); PG8_STAGE(PG8_SA(1, 1), a1 + hstepA, voffA);
;             PG8_WAIT_V(8); PG8_WAIT_L(0); PG8_BAR; PG8_MMA(0, 0, At, B0); PG8_MMA(0, 1, At, B1); PG8_BAR; PG8_SCHED;
;             PG8_LDA(At, 0, 1); PG8_STAGE(PG8_SB(0, 0), b2, voffB); PG8_STAGE(PG8_SB(0, 1), b2 + hstepB, voffB); PG8_STAGE(PG8_SA(0, 0), a2, voffA);
.LBB0_655:
	s_add_u32 s28, s26, 0xfff80080
	s_addc_u32 s29, s27, -1
	s_add_i32 s57, 0, 0x10000
	s_cmp_eq_u32 s56, 28
	s_cselect_b32 s41, s17, s29
	s_cselect_b32 s40, s23, s28
	v_add_u32_e32 v4, s57, v231
	s_cselect_b32 s29, s15, s55
	s_cselect_b32 s28, s25, s34
	s_add_i32 s60, 0, 0x14000
	ds_read_b128 v[134:137], v4
	ds_read_b128 v[138:141], v4 offset:1024
	ds_read_b128 v[142:145], v4 offset:2048
	ds_read_b128 v[146:149], v4 offset:3072
	v_add_u32_e32 v4, s60, v231
	ds_read_b128 v[150:153], v4
	ds_read_b128 v[154:157], v4 offset:1024
	ds_read_b128 v[158:161], v4 offset:2048
	ds_read_b128 v[162:165], v4 offset:3072
	s_add_i32 m0, s47, 0xc000
	ds_read_b128 v[166:169], v235
	ds_read_b128 v[170:173], v235 offset:1024
	ds_read_b128 v[174:177], v235 offset:2048
	ds_read_b128 v[178:181], v235 offset:3072
	ds_read_b128 v[214:217], v235 offset:4096
	ds_read_b128 v[218:221], v235 offset:5120
	ds_read_b128 v[222:225], v235 offset:6144
	ds_read_b128 v[226:229], v235 offset:7168
	global_load_lds_dwordx4 v196, s[26:27]
	s_add_i32 m0, s47, 0xe000
	s_nop 0
	global_load_lds_dwordx4 v212, s[26:27]
	s_waitcnt vmcnt(8)
	s_waitcnt lgkmcnt(0)
	s_barrier
	s_waitcnt lgkmcnt(0)
	v_mfma_f32_16x16x32_bf16 v[130:133], v[134:137], v[166:169], v[130:133]
	v_mfma_f32_16x16x32_bf16 v[126:129], v[142:145], v[166:169], v[126:129]
	v_mfma_f32_16x16x32_bf16 v[114:117], v[134:137], v[174:177], v[114:117]
	v_mfma_f32_16x16x32_bf16 v[110:113], v[142:145], v[174:177], v[110:113]
	v_mfma_f32_16x16x32_bf16 v[98:101], v[134:137], v[214:217], v[98:101]
	v_mfma_f32_16x16x32_bf16 v[94:97], v[142:145], v[214:217], v[94:97]
	v_mfma_f32_16x16x32_bf16 v[82:85], v[134:137], v[222:225], v[82:85]
	v_mfma_f32_16x16x32_bf16 v[78:81], v[142:145], v[222:225], v[78:81]
	v_mfma_f32_16x16x32_bf16 v[130:133], v[138:141], v[170:173], v[130:133]
	v_mfma_f32_16x16x32_bf16 v[126:129], v[146:149], v[170:173], v[126:129]
	v_mfma_f32_16x16x32_bf16 v[114:117], v[138:141], v[178:181], v[114:117]
	v_mfma_f32_16x16x32_bf16 v[110:113], v[146:149], v[178:181], v[110:113]
	v_mfma_f32_16x16x32_bf16 v[98:101], v[138:141], v[218:221], v[98:101]
	v_mfma_f32_16x16x32_bf16 v[94:97], v[146:149], v[218:221], v[94:97]
	v_mfma_f32_16x16x32_bf16 v[82:85], v[138:141], v[226:229], v[82:85]
	v_mfma_f32_16x16x32_bf16 v[78:81], v[146:149], v[226:229], v[78:81]
	v_mfma_f32_16x16x32_bf16 v[122:125], v[150:153], v[166:169], v[122:125]
	v_mfma_f32_16x16x32_bf16 v[118:121], v[158:161], v[166:169], v[118:121]
	v_mfma_f32_16x16x32_bf16 v[106:109], v[150:153], v[174:177], v[106:109]
	v_mfma_f32_16x16x32_bf16 v[102:105], v[158:161], v[174:177], v[102:105]
	v_mfma_f32_16x16x32_bf16 v[90:93], v[150:153], v[214:217], v[90:93]
	v_mfma_f32_16x16x32_bf16 v[86:89], v[158:161], v[214:217], v[86:89]
	v_mfma_f32_16x16x32_bf16 v[74:77], v[150:153], v[222:225], v[74:77]
	v_mfma_f32_16x16x32_bf16 v[70:73], v[158:161], v[222:225], v[70:73]
	v_mfma_f32_16x16x32_bf16 v[122:125], v[154:157], v[170:173], v[122:125]
	v_mfma_f32_16x16x32_bf16 v[118:121], v[162:165], v[170:173], v[118:121]
	v_mfma_f32_16x16x32_bf16 v[106:109], v[154:157], v[178:181], v[106:109]
	v_mfma_f32_16x16x32_bf16 v[102:105], v[162:165], v[178:181], v[102:105]
	v_mfma_f32_16x16x32_bf16 v[90:93], v[154:157], v[218:221], v[90:93]
	v_mfma_f32_16x16x32_bf16 v[86:89], v[162:165], v[218:221], v[86:89]
	v_mfma_f32_16x16x32_bf16 v[74:77], v[154:157], v[226:229], v[74:77]
	v_mfma_f32_16x16x32_bf16 v[70:73], v[162:165], v[226:229], v[70:73]
	s_barrier
	s_add_i32 s57, s57, s46
	v_lshl_add_u64 v[236:237], s[28:29], 0, v[182:183]
	s_mov_b32 m0, s57
	ds_read_b128 v[166:169], v235 offset:16384
	ds_read_b128 v[170:173], v235 offset:17408
	ds_read_b128 v[174:177], v235 offset:18432
	ds_read_b128 v[178:181], v235 offset:19456
	ds_read_b128 v[214:217], v235 offset:20480
	ds_read_b128 v[218:221], v235 offset:21504
	ds_read_b128 v[222:225], v235 offset:22528
	ds_read_b128 v[226:229], v235 offset:23552
	global_load_lds_dwordx4 v[236:237], off
	s_add_i32 m0, s57, 0x2000
	s_add_u32 s58, s28, 0x80000
	v_lshl_add_u64 v[238:239], s[28:29], 0, v[186:187]
	s_addc_u32 s59, s29, 0
	s_add_i32 s57, s60, s46
	global_load_lds_dwordx4 v[238:239], off
	s_mov_b32 m0, s57
	v_lshl_add_u64 v[242:243], s[40:41], 0, v[184:185]
	global_load_lds_dwordx4 v182, s[58:59]
	s_add_i32 m0, s57, 0x2000
	s_nop 0
	global_load_lds_dwordx4 v186, s[58:59]
	v_lshl_add_u64 v[240:241], s[40:41], 0, v[2:3]
	s_mov_b32 m0, s47
	s_nop 0
	global_load_lds_dwordx4 v[240:241], off
	s_mov_b32 m0, s48
	s_nop 0
	global_load_lds_dwordx4 v[242:243], off
	s_waitcnt vmcnt(8)
	s_waitcnt lgkmcnt(0)
	s_barrier
; #define PG8_STAGE(bufoff, gbase, voff) do { _Pragma("unroll") for (int _i = 0; _i < 2; ++_i) \
;         __builtin_amdgcn_global_load_lds((const unsigned*)((const char*)(gbase) + (voff)[_i]), (LAS unsigned*)(lds + (bufoff) + ldsw + _i * 8192), 16, 0, 0); } while (0)
; #define PG8_LDA(dst, b, h) do { _Pragma("unroll") for (int m = 0; m < 4; ++m) _Pragma("unroll") for (int k = 0; k < 2; ++k) dst[m][k] = *(const LAS bf16x8*)(lds + PG8_SA(b, h) + aoff + m * 2048 + k * 1024); } while (0)
; #define PG8_LDB(dst, b, h) do { _Pragma("unroll") for (int n = 0; n < 2; ++n) _Pragma("unroll") for (int k = 0; k < 2; ++k) dst[n][k] = *(const LAS bf16x8*)(lds + PG8_SB(b, h) + boff + n * 2048 + k * 1024); } while (0)
; #define PG8_MMA(ai, bj, At, Bt) do { __builtin_amdgcn_s_setprio(1); _Pragma("unroll") for (int m = 0; m < 4; ++m) _Pragma("unroll") for (int n = 0; n < 2; ++n) _Pragma("unroll") for (int k = 0; k < 2; ++k) \
;         acc[ai][bj][m][n] = __builtin_amdgcn_mfma_f32_16x16x32_bf16(Bt[n][k], At[m][k], acc[ai][bj][m][n], 0, 0, 0); __builtin_amdgcn_s_setprio(0); } while (0)
; #define PG8_WAIT_V(n) asm volatile("s_waitcnt vmcnt(" #n ")" ::: "memory")
; #define PG8_WAIT_L(n) asm volatile("s_waitcnt lgkmcnt(" #n ")" ::: "memory")
; #define PG8_BAR __builtin_amdgcn_s_barrier()
; #define PG8_SCHED __builtin_amdgcn_sched_barrier(0)
; template <class Epi, class Sched>
; __device__ __forceinline__ void gemm_phase(LAS unsigned char* lds, const Gemm g, const Sched& S, const Epi& E) {
;     ...
;             PG8_WAIT_V(8); PG8_WAIT_L(0); PG8_BAR; PG8_MMA(1, 0, At, B0); PG8_MMA(1, 1, At, B1); PG8_BAR; PG8_SCHED;
;             PG8_LDB(B0, 1, 0); PG8_LDB(B1, 1, 1); PG8_SCHED; PG8_LDA(At, 1, 0); PG8_STAGE(PG8_SA(0, 1), a2 + hstepA, voffA);
;             PG8_WAIT_V(8); PG8_WAIT_L(0); PG8_BAR; PG8_MMA(0, 0, At, B0); PG8_MMA(0, 1, At, B1); PG8_BAR; PG8_SCHED;
	s_waitcnt lgkmcnt(0)
	v_mfma_f32_16x16x32_bf16 v[66:69], v[134:137], v[166:169], v[66:69]
	v_mfma_f32_16x16x32_bf16 v[62:65], v[142:145], v[166:169], v[62:65]
	v_mfma_f32_16x16x32_bf16 v[50:53], v[134:137], v[174:177], v[50:53]
	v_mfma_f32_16x16x32_bf16 v[46:49], v[142:145], v[174:177], v[46:49]
	v_mfma_f32_16x16x32_bf16 v[34:37], v[134:137], v[214:217], v[34:37]
	v_mfma_f32_16x16x32_bf16 v[30:33], v[142:145], v[214:217], v[30:33]
	v_mfma_f32_16x16x32_bf16 v[18:21], v[134:137], v[222:225], v[18:21]
	v_mfma_f32_16x16x32_bf16 v[14:17], v[142:145], v[222:225], v[14:17]
	v_mfma_f32_16x16x32_bf16 v[66:69], v[138:141], v[170:173], v[66:69]
	v_mfma_f32_16x16x32_bf16 v[62:65], v[146:149], v[170:173], v[62:65]
	v_mfma_f32_16x16x32_bf16 v[50:53], v[138:141], v[178:181], v[50:53]
	v_mfma_f32_16x16x32_bf16 v[46:49], v[146:149], v[178:181], v[46:49]
	v_mfma_f32_16x16x32_bf16 v[34:37], v[138:141], v[218:221], v[34:37]
	v_mfma_f32_16x16x32_bf16 v[30:33], v[146:149], v[218:221], v[30:33]
	v_mfma_f32_16x16x32_bf16 v[18:21], v[138:141], v[226:229], v[18:21]
	v_mfma_f32_16x16x32_bf16 v[14:17], v[146:149], v[226:229], v[14:17]
	v_mfma_f32_16x16x32_bf16 v[58:61], v[150:153], v[166:169], v[58:61]
	v_mfma_f32_16x16x32_bf16 v[54:57], v[158:161], v[166:169], v[54:57]
	v_mfma_f32_16x16x32_bf16 v[42:45], v[150:153], v[174:177], v[42:45]
	v_mfma_f32_16x16x32_bf16 v[38:41], v[158:161], v[174:177], v[38:41]
	v_mfma_f32_16x16x32_bf16 v[26:29], v[150:153], v[214:217], v[26:29]
	v_mfma_f32_16x16x32_bf16 v[22:25], v[158:161], v[214:217], v[22:25]
	v_mfma_f32_16x16x32_bf16 v[10:13], v[150:153], v[222:225], v[10:13]
	v_mfma_f32_16x16x32_bf16 v[6:9], v[158:161], v[222:225], v[6:9]
	v_mfma_f32_16x16x32_bf16 v[58:61], v[154:157], v[170:173], v[58:61]
	v_mfma_f32_16x16x32_bf16 v[54:57], v[162:165], v[170:173], v[54:57]
	v_mfma_f32_16x16x32_bf16 v[42:45], v[154:157], v[178:181], v[42:45]
	v_mfma_f32_16x16x32_bf16 v[38:41], v[162:165], v[178:181], v[38:41]
	v_mfma_f32_16x16x32_bf16 v[26:29], v[154:157], v[218:221], v[26:29]
	v_mfma_f32_16x16x32_bf16 v[22:25], v[162:165], v[218:221], v[22:25]
	v_mfma_f32_16x16x32_bf16 v[10:13], v[154:157], v[226:229], v[10:13]
	v_mfma_f32_16x16x32_bf16 v[6:9], v[162:165], v[226:229], v[6:9]
	s_barrier
	s_add_i32 s57, 0, 0x18000
	v_add_u32_e32 v4, s57, v231
	s_add_i32 s58, 0, 0x1c000
	ds_read_b128 v[134:137], v4
	ds_read_b128 v[138:141], v4 offset:1024
	ds_read_b128 v[142:145], v4 offset:2048
	ds_read_b128 v[146:149], v4 offset:3072
	v_add_u32_e32 v4, s58, v231
	ds_read_b128 v[150:153], v4
	ds_read_b128 v[154:157], v4 offset:1024
	ds_read_b128 v[158:161], v4 offset:2048
	ds_read_b128 v[162:165], v4 offset:3072
	s_add_u32 s40, s40, 0x80000
	s_addc_u32 s41, s41, 0
	s_mov_b32 m0, s49
	ds_read_b128 v[166:169], v235 offset:32768
	ds_read_b128 v[170:173], v235 offset:33792
	ds_read_b128 v[174:177], v235 offset:34816
	ds_read_b128 v[178:181], v235 offset:35840
	ds_read_b128 v[214:217], v235 offset:36864
	ds_read_b128 v[218:221], v235 offset:37888
	ds_read_b128 v[222:225], v235 offset:38912
	ds_read_b128 v[226:229], v235 offset:39936
	global_load_lds_dwordx4 v2, s[40:41]
	s_mov_b32 m0, s50
	s_nop 0
	global_load_lds_dwordx4 v184, s[40:41]
	s_waitcnt vmcnt(8)
	s_waitcnt lgkmcnt(0)
	s_barrier
	s_waitcnt lgkmcnt(0)
	v_mfma_f32_16x16x32_bf16 v[130:133], v[134:137], v[166:169], v[130:133]
	v_mfma_f32_16x16x32_bf16 v[126:129], v[142:145], v[166:169], v[126:129]
	v_mfma_f32_16x16x32_bf16 v[114:117], v[134:137], v[174:177], v[114:117]
	v_mfma_f32_16x16x32_bf16 v[110:113], v[142:145], v[174:177], v[110:113]
	v_mfma_f32_16x16x32_bf16 v[98:101], v[134:137], v[214:217], v[98:101]
	v_mfma_f32_16x16x32_bf16 v[94:97], v[142:145], v[214:217], v[94:97]
	v_mfma_f32_16x16x32_bf16 v[82:85], v[134:137], v[222:225], v[82:85]
	v_mfma_f32_16x16x32_bf16 v[78:81], v[142:145], v[222:225], v[78:81]
	v_mfma_f32_16x16x32_bf16 v[130:133], v[138:141], v[170:173], v[130:133]
	v_mfma_f32_16x16x32_bf16 v[126:129], v[146:149], v[170:173], v[126:129]
	v_mfma_f32_16x16x32_bf16 v[114:117], v[138:141], v[178:181], v[114:117]
	v_mfma_f32_16x16x32_bf16 v[110:113], v[146:149], v[178:181], v[110:113]
	v_mfma_f32_16x16x32_bf16 v[98:101], v[138:141], v[218:221], v[98:101]
	v_mfma_f32_16x16x32_bf16 v[94:97], v[146:149], v[218:221], v[94:97]
	v_mfma_f32_16x16x32_bf16 v[82:85], v[138:141], v[226:229], v[82:85]
	v_mfma_f32_16x16x32_bf16 v[78:81], v[146:149], v[226:229], v[78:81]
	v_mfma_f32_16x16x32_bf16 v[122:125], v[150:153], v[166:169], v[122:125]
	v_mfma_f32_16x16x32_bf16 v[118:121], v[158:161], v[166:169], v[118:121]
	v_mfma_f32_16x16x32_bf16 v[106:109], v[150:153], v[174:177], v[106:109]
	v_mfma_f32_16x16x32_bf16 v[102:105], v[158:161], v[174:177], v[102:105]
	v_mfma_f32_16x16x32_bf16 v[90:93], v[150:153], v[214:217], v[90:93]
	v_mfma_f32_16x16x32_bf16 v[86:89], v[158:161], v[214:217], v[86:89]
	v_mfma_f32_16x16x32_bf16 v[74:77], v[150:153], v[222:225], v[74:77]
	v_mfma_f32_16x16x32_bf16 v[70:73], v[158:161], v[222:225], v[70:73]
	v_mfma_f32_16x16x32_bf16 v[122:125], v[154:157], v[170:173], v[122:125]
	v_mfma_f32_16x16x32_bf16 v[118:121], v[162:165], v[170:173], v[118:121]
	v_mfma_f32_16x16x32_bf16 v[106:109], v[154:157], v[178:181], v[106:109]
	v_mfma_f32_16x16x32_bf16 v[102:105], v[162:165], v[178:181], v[102:105]
	v_mfma_f32_16x16x32_bf16 v[90:93], v[154:157], v[218:221], v[90:93]
	v_mfma_f32_16x16x32_bf16 v[86:89], v[162:165], v[218:221], v[86:89]
	v_mfma_f32_16x16x32_bf16 v[74:77], v[154:157], v[226:229], v[74:77]
	v_mfma_f32_16x16x32_bf16 v[70:73], v[162:165], v[226:229], v[70:73]
	s_barrier
; #define PG8_STAGE(bufoff, gbase, voff) do { _Pragma("unroll") for (int _i = 0; _i < 2; ++_i) \
;         __builtin_amdgcn_global_load_lds((const unsigned*)((const char*)(gbase) + (voff)[_i]), (LAS unsigned*)(lds + (bufoff) + ldsw + _i * 8192), 16, 0, 0); } while (0)
; #define PG8_LDA(dst, b, h) do { _Pragma("unroll") for (int m = 0; m < 4; ++m) _Pragma("unroll") for (int k = 0; k < 2; ++k) dst[m][k] = *(const LAS bf16x8*)(lds + PG8_SA(b, h) + aoff + m * 2048 + k * 1024); } while (0)
; #define PG8_MMA(ai, bj, At, Bt) do { __builtin_amdgcn_s_setprio(1); _Pragma("unroll") for (int m = 0; m < 4; ++m) _Pragma("unroll") for (int n = 0; n < 2; ++n) _Pragma("unroll") for (int k = 0; k < 2; ++k) \
;         acc[ai][bj][m][n] = __builtin_amdgcn_mfma_f32_16x16x32_bf16(Bt[n][k], At[m][k], acc[ai][bj][m][n], 0, 0, 0); __builtin_amdgcn_s_setprio(0); } while (0)
; #define PG8_WAIT_V(n) asm volatile("s_waitcnt vmcnt(" #n ")" ::: "memory")
; #define PG8_WAIT_L(n) asm volatile("s_waitcnt lgkmcnt(" #n ")" ::: "memory")
; #define PG8_BAR __builtin_amdgcn_s_barrier()
; #define PG8_SCHED __builtin_amdgcn_sched_barrier(0)
; template <class Epi, class Sched>
; __device__ __forceinline__ void gemm_phase(LAS unsigned char* lds, const Gemm g, const Sched& S, const Epi& E) {
;     ...
;             PG8_LDA(At, 1, 1); PG8_STAGE(PG8_SB(1, 0), b3, voffB); PG8_STAGE(PG8_SB(1, 1), b3 + hstepB, voffB); PG8_STAGE(PG8_SA(1, 0), a3, voffA);
;             PG8_WAIT_V(8); PG8_WAIT_L(0); PG8_BAR; PG8_MMA(1, 0, At, B0); PG8_MMA(1, 1, At, B1); PG8_BAR; PG8_SCHED;
;         }
	s_add_i32 s40, s57, s46
	s_add_i32 m0, s40, 0xffffff80
	ds_read_b128 v[166:169], v235 offset:49152
	ds_read_b128 v[170:173], v235 offset:50176
	ds_read_b128 v[174:177], v235 offset:51200
	ds_read_b128 v[178:181], v235 offset:52224
	ds_read_b128 v[214:217], v235 offset:53248
	ds_read_b128 v[218:221], v235 offset:54272
	ds_read_b128 v[222:225], v235 offset:55296
	ds_read_b128 v[226:229], v235 offset:56320
	global_load_lds_dwordx4 v[236:237], off offset:128
	s_add_i32 m0, s40, 0x1f80
	s_add_u32 s28, s28, 0x80080
	s_addc_u32 s29, s29, 0
	s_add_i32 s40, s58, s46
	global_load_lds_dwordx4 v[238:239], off offset:128
	s_mov_b32 m0, s40
	s_nop 0
	global_load_lds_dwordx4 v182, s[28:29]
	s_add_i32 m0, s40, 0x2000
	s_nop 0
	global_load_lds_dwordx4 v186, s[28:29]
	s_add_i32 m0, s52, 0xffffff80
	s_nop 0
	global_load_lds_dwordx4 v[240:241], off offset:128
	s_add_i32 m0, s53, 0xffffff80
	s_nop 0
	global_load_lds_dwordx4 v[242:243], off offset:128
	s_waitcnt vmcnt(8)
	s_waitcnt lgkmcnt(0)
	s_barrier
	s_waitcnt lgkmcnt(0)
	v_mfma_f32_16x16x32_bf16 v[66:69], v[134:137], v[166:169], v[66:69]
	v_mfma_f32_16x16x32_bf16 v[62:65], v[142:145], v[166:169], v[62:65]
	v_mfma_f32_16x16x32_bf16 v[50:53], v[134:137], v[174:177], v[50:53]
	v_mfma_f32_16x16x32_bf16 v[46:49], v[142:145], v[174:177], v[46:49]
	v_mfma_f32_16x16x32_bf16 v[34:37], v[134:137], v[214:217], v[34:37]
	v_mfma_f32_16x16x32_bf16 v[30:33], v[142:145], v[214:217], v[30:33]
	v_mfma_f32_16x16x32_bf16 v[18:21], v[134:137], v[222:225], v[18:21]
	v_mfma_f32_16x16x32_bf16 v[14:17], v[142:145], v[222:225], v[14:17]
	v_mfma_f32_16x16x32_bf16 v[66:69], v[138:141], v[170:173], v[66:69]
	v_mfma_f32_16x16x32_bf16 v[62:65], v[146:149], v[170:173], v[62:65]
	v_mfma_f32_16x16x32_bf16 v[50:53], v[138:141], v[178:181], v[50:53]
	v_mfma_f32_16x16x32_bf16 v[46:49], v[146:149], v[178:181], v[46:49]
	v_mfma_f32_16x16x32_bf16 v[34:37], v[138:141], v[218:221], v[34:37]
	v_mfma_f32_16x16x32_bf16 v[30:33], v[146:149], v[218:221], v[30:33]
	v_mfma_f32_16x16x32_bf16 v[18:21], v[138:141], v[226:229], v[18:21]
	v_mfma_f32_16x16x32_bf16 v[14:17], v[146:149], v[226:229], v[14:17]
	v_mfma_f32_16x16x32_bf16 v[58:61], v[150:153], v[166:169], v[58:61]
	v_mfma_f32_16x16x32_bf16 v[54:57], v[158:161], v[166:169], v[54:57]
	v_mfma_f32_16x16x32_bf16 v[42:45], v[150:153], v[174:177], v[42:45]
	v_mfma_f32_16x16x32_bf16 v[38:41], v[158:161], v[174:177], v[38:41]
	v_mfma_f32_16x16x32_bf16 v[26:29], v[150:153], v[214:217], v[26:29]
	v_mfma_f32_16x16x32_bf16 v[22:25], v[158:161], v[214:217], v[22:25]
	v_mfma_f32_16x16x32_bf16 v[10:13], v[150:153], v[222:225], v[10:13]
	v_mfma_f32_16x16x32_bf16 v[6:9], v[158:161], v[222:225], v[6:9]
	v_mfma_f32_16x16x32_bf16 v[58:61], v[154:157], v[170:173], v[58:61]
	v_mfma_f32_16x16x32_bf16 v[54:57], v[162:165], v[170:173], v[54:57]
	v_mfma_f32_16x16x32_bf16 v[42:45], v[154:157], v[178:181], v[42:45]
	v_mfma_f32_16x16x32_bf16 v[38:41], v[162:165], v[178:181], v[38:41]
	v_mfma_f32_16x16x32_bf16 v[26:29], v[154:157], v[218:221], v[26:29]
	v_mfma_f32_16x16x32_bf16 v[22:25], v[162:165], v[218:221], v[22:25]
	v_mfma_f32_16x16x32_bf16 v[10:13], v[154:157], v[226:229], v[10:13]
	v_mfma_f32_16x16x32_bf16 v[6:9], v[162:165], v[226:229], v[6:9]
	s_barrier
	s_add_i32 s56, s56, 2
	s_add_u32 s26, s26, 0x100
	s_addc_u32 s27, s27, 0
	s_add_u32 s34, s34, 0x100
	s_addc_u32 s55, s55, 0
	s_cmp_gt_u32 s56, 29
	s_cbranch_scc0 .LBB0_655
	s_and_b64 vcc, exec, s[12:13]
	s_cbranch_vccz .LBB0_658
	s_barrier

; #define PG8_STAGE(bufoff, gbase, voff) do { _Pragma("unroll") for (int _i = 0; _i < 2; ++_i) \
;         __builtin_amdgcn_global_load_lds((const unsigned*)((const char*)(gbase) + (voff)[_i]), (LAS unsigned*)(lds + (bufoff) + ldsw + _i * 8192), 16, 0, 0); } while (0)
; #define PG8_WAIT_V(n) asm volatile("s_waitcnt vmcnt(" #n ")" ::: "memory")
; #define PG8_BAR __builtin_amdgcn_s_barrier()
; template <class Epi, class Sched>
; __device__ __forceinline__ void gemm_phase(LAS unsigned char* lds, const Gemm g, const Sched& S, const Epi& E) {
;     ...
;     f32x4 acc[2][2][4][2];
; #pragma unroll
;     for (int a = 0; a < 2; ++a)
; #pragma unroll
;         for (int b = 0; b < 2; ++b)
; #pragma unroll
;             for (int m = 0; m < 4; ++m)
; #pragma unroll
;                 for (int n = 0; n < 2; ++n) acc[a][b][m][n] = (f32x4){0.f, 0.f, 0.f, 0.f};
;     bf16x8 At[4][2], B0[2][2], B1[2][2];
;     const char* cA = (const char*)g.A + (size_t)cur.pm * tstepA + (size_t)cur.ka * 2; const char* cB = (const char*)g.Bt + (size_t)cur.pn * tstepB;
;     S.a_ready(cur);
;     PG8_STAGE(PG8_SB(0, 0), cB, voffB); PG8_STAGE(PG8_SB(0, 1), cB + hstepB, voffB); PG8_STAGE(PG8_SA(0, 0), cA, voffA); PG8_STAGE(PG8_SA(0, 1), cA + hstepA, voffA);
;     if (wr == 1) PG8_BAR;
;     PG8_WAIT_V(2); PG8_BAR;
;     PG8_STAGE(PG8_SB(1, 0), cB + kstep, voffB); PG8_STAGE(PG8_SA(1, 0), cA + kstep, voffA); PG8_STAGE(PG8_SB(1, 1), cB + hstepB + kstep, voffB);
;     PG8_WAIT_V(6); PG8_BAR;
.LBB0_995:
	v_mov_b32_e32 v139, v5
	v_lshl_add_u64 v[10:11], s[24:25], 0, v[138:139]
	v_mov_b32_e32 v135, v5
	v_lshl_add_u64 v[12:13], s[24:25], 0, v[134:135]
	v_mov_b32_e32 v141, v5
	s_add_i32 m0, s58, 0x18000
	v_lshl_add_u64 v[10:11], v[10:11], 0, s[36:37]
	v_lshl_add_u64 v[18:19], s[26:27], 0, v[140:141]
	v_mov_b32_e32 v137, v5
	s_waitcnt vmcnt(2)
	s_barrier
	global_load_lds_dwordx4 v[10:11], off
	v_lshl_add_u64 v[10:11], v[12:13], 0, s[36:37]
	s_add_i32 m0, s58, 0x1a000
	s_add_i32 s62, s58, 0x8000
	v_lshl_add_u64 v[20:21], s[26:27], 0, v[136:137]
	global_load_lds_dwordx4 v[10:11], off
	v_lshl_add_u64 v[10:11], v[18:19], 0, s[36:37]
	s_mov_b32 m0, s62
	s_add_i32 s63, s58, 0xa000
	v_lshl_add_u64 v[14:15], s[4:5], 0, v[138:139]
	global_load_lds_dwordx4 v[10:11], off
	v_lshl_add_u64 v[10:11], v[20:21], 0, s[36:37]
	s_mov_b32 m0, s63
	v_lshl_add_u64 v[16:17], s[4:5], 0, v[134:135]
	global_load_lds_dwordx4 v[10:11], off
	s_add_i32 m0, s58, 0x1c000
	v_lshl_add_u64 v[10:11], v[14:15], 0, s[36:37]
	global_load_lds_dwordx4 v[10:11], off
	v_lshl_add_u64 v[10:11], v[16:17], 0, s[36:37]
	s_add_i32 m0, s58, 0x1e000
	v_and_b32_e32 v168, 15, v169
	global_load_lds_dwordx4 v[10:11], off
	v_and_b32_e32 v9, 48, v169
	v_lshlrev_b32_e32 v10, 2, v169
	s_and_b32 s54, s50, 3
	s_lshr_b32 s64, s6, 6
	v_lshl_or_b32 v9, v168, 6, v9
	s_lshl_b32 s4, s52, 13
	v_and_b32_e32 v10, 32, v10
	v_bitop3_b32 v11, v9, s4, v10 bitop3:0xde
	s_lshl_b32 s4, s54, 12
	s_add_i32 s65, s64, -2
	s_cmpk_lt_u32 s51, 0x100
	v_bitop3_b32 v148, v9, s4, v10 bitop3:0xde
	s_cselect_b64 s[28:29], -1, 0
	s_add_u32 s4, s34, 0x80
	v_add_u32_e32 v4, v8, v4
	s_addc_u32 s5, 0, 0
	v_add_lshl_u32 v4, v4, v7, 1
	v_add_u32_e32 v2, v6, v2
	v_lshl_add_u64 v[142:143], s[4:5], 0, v[4:5]
	v_add_lshl_u32 v4, v2, v3, 1
	s_waitcnt vmcnt(6)
	v_lshl_add_u64 v[144:145], s[4:5], 0, v[4:5]
	v_mov_b32_e32 v4, v5
	v_mov_b32_e32 v2, v5
	v_mov_b32_e32 v3, v5
	v_add_u32_e32 v149, 0, v11
	v_mov_b64_e32 v[8:9], v[4:5]
	v_mov_b64_e32 v[12:13], v[4:5]
	v_mov_b64_e32 v[16:17], v[4:5]
	v_mov_b64_e32 v[20:21], v[4:5]
	v_mov_b64_e32 v[24:25], v[4:5]
	v_mov_b64_e32 v[32:33], v[4:5]
	v_mov_b64_e32 v[40:41], v[4:5]
	v_mov_b64_e32 v[48:49], v[4:5]
	v_mov_b64_e32 v[28:29], v[4:5]
	v_mov_b64_e32 v[36:37], v[4:5]
	v_mov_b64_e32 v[44:45], v[4:5]
	v_mov_b64_e32 v[52:53], v[4:5]
	v_mov_b64_e32 v[56:57], v[4:5]
	v_mov_b64_e32 v[60:61], v[4:5]
	v_mov_b64_e32 v[64:65], v[4:5]
	v_mov_b64_e32 v[68:69], v[4:5]
	v_mov_b64_e32 v[72:73], v[4:5]
	v_mov_b64_e32 v[76:77], v[4:5]
	v_mov_b64_e32 v[80:81], v[4:5]
	v_mov_b64_e32 v[84:85], v[4:5]
	v_mov_b64_e32 v[88:89], v[4:5]
	v_mov_b64_e32 v[96:97], v[4:5]
	v_mov_b64_e32 v[104:105], v[4:5]
	v_mov_b64_e32 v[116:117], v[4:5]
	v_mov_b64_e32 v[92:93], v[4:5]
	v_mov_b64_e32 v[100:101], v[4:5]
	v_mov_b64_e32 v[108:109], v[4:5]
	v_mov_b64_e32 v[112:113], v[4:5]
	v_mov_b64_e32 v[120:121], v[4:5]
	v_mov_b64_e32 v[124:125], v[4:5]
	v_mov_b64_e32 v[128:129], v[4:5]
	v_mov_b64_e32 v[132:133], v[4:5]
	v_readlane_b32 s4, v254, 13
	s_mov_b32 s66, 0
	v_mov_b64_e32 v[6:7], v[2:3]
	v_mov_b64_e32 v[10:11], v[2:3]
	v_mov_b64_e32 v[14:15], v[2:3]
	v_mov_b64_e32 v[18:19], v[2:3]
	v_mov_b64_e32 v[22:23], v[2:3]
	v_mov_b64_e32 v[30:31], v[2:3]
	v_mov_b64_e32 v[38:39], v[2:3]
	v_mov_b64_e32 v[46:47], v[2:3]
	v_mov_b64_e32 v[26:27], v[2:3]
	v_mov_b64_e32 v[34:35], v[2:3]
	v_mov_b64_e32 v[42:43], v[2:3]
	v_mov_b64_e32 v[50:51], v[2:3]
	v_mov_b64_e32 v[54:55], v[2:3]
	v_mov_b64_e32 v[58:59], v[2:3]
	v_mov_b64_e32 v[62:63], v[2:3]
	v_mov_b64_e32 v[66:67], v[2:3]
	v_mov_b64_e32 v[70:71], v[2:3]
	v_mov_b64_e32 v[74:75], v[2:3]
	v_mov_b64_e32 v[78:79], v[2:3]
	v_mov_b64_e32 v[82:83], v[2:3]
	v_mov_b64_e32 v[86:87], v[2:3]
	v_mov_b64_e32 v[94:95], v[2:3]
	v_mov_b64_e32 v[102:103], v[2:3]
	v_mov_b64_e32 v[114:115], v[2:3]
	v_mov_b64_e32 v[90:91], v[2:3]
	v_mov_b64_e32 v[98:99], v[2:3]
	v_mov_b64_e32 v[106:107], v[2:3]
	v_mov_b64_e32 v[110:111], v[2:3]
	v_mov_b64_e32 v[118:119], v[2:3]
	v_mov_b64_e32 v[122:123], v[2:3]
	v_mov_b64_e32 v[126:127], v[2:3]
	v_mov_b64_e32 v[130:131], v[2:3]
	s_mov_b32 s6, s4
	v_readlane_b32 s53, v253, 61
	s_barrier
	s_branch .LBB0_998
	s_nop 0
	s_nop 0
	s_nop 0
	s_nop 0
	s_nop 0
	s_nop 0
	s_nop 0
	s_nop 0
	s_nop 0
	s_nop 0
	s_nop 0
	s_nop 0

; #define PG8_STAGE(bufoff, gbase, voff) do { _Pragma("unroll") for (int _i = 0; _i < 2; ++_i) \
;         __builtin_amdgcn_global_load_lds((const unsigned*)((const char*)(gbase) + (voff)[_i]), (LAS unsigned*)(lds + (bufoff) + ldsw + _i * 8192), 16, 0, 0); } while (0)
; #define PG8_LDA(dst, b, h) do { _Pragma("unroll") for (int m = 0; m < 4; ++m) _Pragma("unroll") for (int k = 0; k < 2; ++k) dst[m][k] = *(const LAS bf16x8*)(lds + PG8_SA(b, h) + aoff + m * 2048 + k * 1024); } while (0)
; #define PG8_LDB(dst, b, h) do { _Pragma("unroll") for (int n = 0; n < 2; ++n) _Pragma("unroll") for (int k = 0; k < 2; ++k) dst[n][k] = *(const LAS bf16x8*)(lds + PG8_SB(b, h) + boff + n * 2048 + k * 1024); } while (0)
; #define PG8_MMA(ai, bj, At, Bt) do { __builtin_amdgcn_s_setprio(1); _Pragma("unroll") for (int m = 0; m < 4; ++m) _Pragma("unroll") for (int n = 0; n < 2; ++n) _Pragma("unroll") for (int k = 0; k < 2; ++k) \
;         acc[ai][bj][m][n] = __builtin_amdgcn_mfma_f32_16x16x32_bf16(Bt[n][k], At[m][k], acc[ai][bj][m][n], 0, 0, 0); __builtin_amdgcn_s_setprio(0); } while (0)
; #define PG8_WAIT_V(n) asm volatile("s_waitcnt vmcnt(" #n ")" ::: "memory")
; #define PG8_WAIT_L(n) asm volatile("s_waitcnt lgkmcnt(" #n ")" ::: "memory")
; #define PG8_BAR __builtin_amdgcn_s_barrier()
; #define PG8_SCHED __builtin_amdgcn_sched_barrier(0)
; template <class Epi, class Sched>
; __device__ __forceinline__ void gemm_phase(LAS unsigned char* lds, const Gemm g, const Sched& S, const Epi& E) {
;     ...
;             const bool last = (t == nt - 2);
;             const char* a1 = cA + (size_t)(t + 1) * kstep;
;             const char* a2 = last ? nA : cA + (size_t)(t + 2) * kstep; const char* b2 = last ? nB : cB + (size_t)(t + 2) * kstep;
;             const char* a3 = a2 + kstep; const char* b3 = b2 + kstep;
;             if (last && has_next) S.a_ready(nxt);
;             PG8_LDB(B0, 0, 0); PG8_LDB(B1, 0, 1); PG8_SCHED; PG8_LDA(At, 0, 0); PG8_STAGE(PG8_SA(1, 1), a1 + hstepA, voffA);
;             PG8_WAIT_V(8); PG8_WAIT_L(0); PG8_BAR; PG8_MMA(0, 0, At, B0); PG8_MMA(0, 1, At, B1); PG8_BAR; PG8_SCHED;
;             PG8_LDA(At, 0, 1); PG8_STAGE(PG8_SB(0, 0), b2, voffB); PG8_STAGE(PG8_SB(0, 1), b2 + hstepB, voffB); PG8_STAGE(PG8_SA(0, 0), a2, voffA);
.LBB0_1009:
	s_add_i32 s43, s48, 2
	s_add_u32 s70, s26, s46
	s_addc_u32 s49, s27, s47
	s_add_u32 s72, s24, s46
	s_addc_u32 s71, s25, s47
	s_add_i32 s73, 0, 0x10000
	s_cmp_eq_u32 s65, s48
	s_cselect_b32 s49, s5, s49
	s_cselect_b32 s48, s4, s70
	v_add_u32_e32 v4, s73, v148
	s_cselect_b32 s71, s45, s71
	s_cselect_b32 s70, s44, s72
	s_add_i32 s72, 0, 0x14000
	ds_read_b128 v[150:153], v4
	ds_read_b128 v[154:157], v4 offset:1024
	ds_read_b128 v[158:161], v4 offset:2048
	ds_read_b128 v[162:165], v4 offset:3072
	v_add_u32_e32 v4, s72, v148
	ds_read_b128 v[170:173], v4
	ds_read_b128 v[174:177], v4 offset:1024
	ds_read_b128 v[178:181], v4 offset:2048
	ds_read_b128 v[182:185], v4 offset:3072
	v_lshl_add_u64 v[166:167], s[26:27], 0, v[146:147]
	s_add_i32 m0, s58, 0xc000
	ds_read_b128 v[186:189], v149
	ds_read_b128 v[190:193], v149 offset:1024
	ds_read_b128 v[194:197], v149 offset:2048
	ds_read_b128 v[212:215], v149 offset:3072
	ds_read_b128 v[216:219], v149 offset:4096
	ds_read_b128 v[220:223], v149 offset:5120
	ds_read_b128 v[224:227], v149 offset:6144
	ds_read_b128 v[228:231], v149 offset:7168
	global_load_lds_dwordx4 v[166:167], off
	v_lshl_add_u64 v[166:167], s[26:27], 0, v[2:3]
	s_add_i32 m0, s58, 0xe000
	s_nop 0
	global_load_lds_dwordx4 v[166:167], off
	s_waitcnt vmcnt(8)
	s_waitcnt lgkmcnt(0)
	s_barrier
	s_waitcnt lgkmcnt(0)
	v_mfma_f32_16x16x32_bf16 v[130:133], v[150:153], v[186:189], v[130:133]
	v_mfma_f32_16x16x32_bf16 v[126:129], v[158:161], v[186:189], v[126:129]
	v_mfma_f32_16x16x32_bf16 v[122:125], v[150:153], v[194:197], v[122:125]
	v_mfma_f32_16x16x32_bf16 v[118:121], v[158:161], v[194:197], v[118:121]
	v_mfma_f32_16x16x32_bf16 v[110:113], v[150:153], v[216:219], v[110:113]
	v_mfma_f32_16x16x32_bf16 v[106:109], v[158:161], v[216:219], v[106:109]
	v_mfma_f32_16x16x32_bf16 v[98:101], v[150:153], v[224:227], v[98:101]
	v_mfma_f32_16x16x32_bf16 v[90:93], v[158:161], v[224:227], v[90:93]
	v_mfma_f32_16x16x32_bf16 v[130:133], v[154:157], v[190:193], v[130:133]
	v_mfma_f32_16x16x32_bf16 v[126:129], v[162:165], v[190:193], v[126:129]
	v_mfma_f32_16x16x32_bf16 v[122:125], v[154:157], v[212:215], v[122:125]
	v_mfma_f32_16x16x32_bf16 v[118:121], v[162:165], v[212:215], v[118:121]
	v_mfma_f32_16x16x32_bf16 v[110:113], v[154:157], v[220:223], v[110:113]
	v_mfma_f32_16x16x32_bf16 v[106:109], v[162:165], v[220:223], v[106:109]
	v_mfma_f32_16x16x32_bf16 v[98:101], v[154:157], v[228:231], v[98:101]
	v_mfma_f32_16x16x32_bf16 v[90:93], v[162:165], v[228:231], v[90:93]
	v_mfma_f32_16x16x32_bf16 v[114:117], v[170:173], v[186:189], v[114:117]
	v_mfma_f32_16x16x32_bf16 v[102:105], v[178:181], v[186:189], v[102:105]
	v_mfma_f32_16x16x32_bf16 v[94:97], v[170:173], v[194:197], v[94:97]
	v_mfma_f32_16x16x32_bf16 v[86:89], v[178:181], v[194:197], v[86:89]
	v_mfma_f32_16x16x32_bf16 v[82:85], v[170:173], v[216:219], v[82:85]
	v_mfma_f32_16x16x32_bf16 v[78:81], v[178:181], v[216:219], v[78:81]
	v_mfma_f32_16x16x32_bf16 v[74:77], v[170:173], v[224:227], v[74:77]
	v_mfma_f32_16x16x32_bf16 v[70:73], v[178:181], v[224:227], v[70:73]
	v_mfma_f32_16x16x32_bf16 v[114:117], v[174:177], v[190:193], v[114:117]
	v_mfma_f32_16x16x32_bf16 v[102:105], v[182:185], v[190:193], v[102:105]
	v_mfma_f32_16x16x32_bf16 v[94:97], v[174:177], v[212:215], v[94:97]
	v_mfma_f32_16x16x32_bf16 v[86:89], v[182:185], v[212:215], v[86:89]
	v_mfma_f32_16x16x32_bf16 v[82:85], v[174:177], v[220:223], v[82:85]
	v_mfma_f32_16x16x32_bf16 v[78:81], v[182:185], v[220:223], v[78:81]
	v_mfma_f32_16x16x32_bf16 v[74:77], v[174:177], v[228:231], v[74:77]
	v_mfma_f32_16x16x32_bf16 v[70:73], v[182:185], v[228:231], v[70:73]
	s_barrier
	s_add_i32 s73, s73, s57
	v_lshl_add_u64 v[166:167], s[70:71], 0, v[138:139]
	s_mov_b32 m0, s73
	ds_read_b128 v[186:189], v149 offset:16384
	ds_read_b128 v[190:193], v149 offset:17408
	ds_read_b128 v[194:197], v149 offset:18432
	ds_read_b128 v[212:215], v149 offset:19456
	ds_read_b128 v[216:219], v149 offset:20480
	ds_read_b128 v[220:223], v149 offset:21504
	ds_read_b128 v[224:227], v149 offset:22528
	ds_read_b128 v[228:231], v149 offset:23552
	global_load_lds_dwordx4 v[166:167], off
	s_add_i32 m0, s73, 0x2000
	v_lshl_add_u64 v[236:237], s[70:71], 0, v[134:135]
	s_add_u32 s70, s70, s55
	s_addc_u32 s71, s71, 0
	s_add_i32 s72, s72, s57
	global_load_lds_dwordx4 v[236:237], off
	v_lshl_add_u64 v[238:239], s[70:71], 0, v[138:139]
	s_mov_b32 m0, s72
	v_lshl_add_u64 v[240:241], s[70:71], 0, v[134:135]
	global_load_lds_dwordx4 v[238:239], off
	s_add_i32 m0, s72, 0x2000
	v_lshl_add_u64 v[242:243], s[48:49], 0, v[140:141]
	global_load_lds_dwordx4 v[240:241], off
	s_mov_b32 m0, s58
	v_lshl_add_u64 v[244:245], s[48:49], 0, v[136:137]
	global_load_lds_dwordx4 v[242:243], off
	s_mov_b32 m0, s59
	s_nop 0
	global_load_lds_dwordx4 v[244:245], off
	s_waitcnt vmcnt(8)
	s_waitcnt lgkmcnt(0)
	s_barrier
; #define PG8_STAGE(bufoff, gbase, voff) do { _Pragma("unroll") for (int _i = 0; _i < 2; ++_i) \
;         __builtin_amdgcn_global_load_lds((const unsigned*)((const char*)(gbase) + (voff)[_i]), (LAS unsigned*)(lds + (bufoff) + ldsw + _i * 8192), 16, 0, 0); } while (0)
; #define PG8_LDA(dst, b, h) do { _Pragma("unroll") for (int m = 0; m < 4; ++m) _Pragma("unroll") for (int k = 0; k < 2; ++k) dst[m][k] = *(const LAS bf16x8*)(lds + PG8_SA(b, h) + aoff + m * 2048 + k * 1024); } while (0)
; #define PG8_LDB(dst, b, h) do { _Pragma("unroll") for (int n = 0; n < 2; ++n) _Pragma("unroll") for (int k = 0; k < 2; ++k) dst[n][k] = *(const LAS bf16x8*)(lds + PG8_SB(b, h) + boff + n * 2048 + k * 1024); } while (0)
; #define PG8_MMA(ai, bj, At, Bt) do { __builtin_amdgcn_s_setprio(1); _Pragma("unroll") for (int m = 0; m < 4; ++m) _Pragma("unroll") for (int n = 0; n < 2; ++n) _Pragma("unroll") for (int k = 0; k < 2; ++k) \
;         acc[ai][bj][m][n] = __builtin_amdgcn_mfma_f32_16x16x32_bf16(Bt[n][k], At[m][k], acc[ai][bj][m][n], 0, 0, 0); __builtin_amdgcn_s_setprio(0); } while (0)
; #define PG8_WAIT_V(n) asm volatile("s_waitcnt vmcnt(" #n ")" ::: "memory")
; #define PG8_WAIT_L(n) asm volatile("s_waitcnt lgkmcnt(" #n ")" ::: "memory")
; #define PG8_BAR __builtin_amdgcn_s_barrier()
; #define PG8_SCHED __builtin_amdgcn_sched_barrier(0)
; template <class Epi, class Sched>
; __device__ __forceinline__ void gemm_phase(LAS unsigned char* lds, const Gemm g, const Sched& S, const Epi& E) {
;     ...
;             PG8_WAIT_V(8); PG8_WAIT_L(0); PG8_BAR; PG8_MMA(1, 0, At, B0); PG8_MMA(1, 1, At, B1); PG8_BAR; PG8_SCHED;
;             PG8_LDB(B0, 1, 0); PG8_LDB(B1, 1, 1); PG8_SCHED; PG8_LDA(At, 1, 0); PG8_STAGE(PG8_SA(0, 1), a2 + hstepA, voffA);
;             PG8_WAIT_V(8); PG8_WAIT_L(0); PG8_BAR; PG8_MMA(0, 0, At, B0); PG8_MMA(0, 1, At, B1); PG8_BAR; PG8_SCHED;
	s_waitcnt lgkmcnt(0)
	v_mfma_f32_16x16x32_bf16 v[66:69], v[150:153], v[186:189], v[66:69]
	v_mfma_f32_16x16x32_bf16 v[62:65], v[158:161], v[186:189], v[62:65]
	v_mfma_f32_16x16x32_bf16 v[58:61], v[150:153], v[194:197], v[58:61]
	v_mfma_f32_16x16x32_bf16 v[54:57], v[158:161], v[194:197], v[54:57]
	v_mfma_f32_16x16x32_bf16 v[50:53], v[150:153], v[216:219], v[50:53]
	v_mfma_f32_16x16x32_bf16 v[42:45], v[158:161], v[216:219], v[42:45]
	v_mfma_f32_16x16x32_bf16 v[34:37], v[150:153], v[224:227], v[34:37]
	v_mfma_f32_16x16x32_bf16 v[26:29], v[158:161], v[224:227], v[26:29]
	v_mfma_f32_16x16x32_bf16 v[66:69], v[154:157], v[190:193], v[66:69]
	v_mfma_f32_16x16x32_bf16 v[62:65], v[162:165], v[190:193], v[62:65]
	v_mfma_f32_16x16x32_bf16 v[58:61], v[154:157], v[212:215], v[58:61]
	v_mfma_f32_16x16x32_bf16 v[54:57], v[162:165], v[212:215], v[54:57]
	v_mfma_f32_16x16x32_bf16 v[50:53], v[154:157], v[220:223], v[50:53]
	v_mfma_f32_16x16x32_bf16 v[42:45], v[162:165], v[220:223], v[42:45]
	v_mfma_f32_16x16x32_bf16 v[34:37], v[154:157], v[228:231], v[34:37]
	v_mfma_f32_16x16x32_bf16 v[26:29], v[162:165], v[228:231], v[26:29]
	v_mfma_f32_16x16x32_bf16 v[46:49], v[170:173], v[186:189], v[46:49]
	v_mfma_f32_16x16x32_bf16 v[38:41], v[178:181], v[186:189], v[38:41]
	v_mfma_f32_16x16x32_bf16 v[30:33], v[170:173], v[194:197], v[30:33]
	v_mfma_f32_16x16x32_bf16 v[22:25], v[178:181], v[194:197], v[22:25]
	v_mfma_f32_16x16x32_bf16 v[18:21], v[170:173], v[216:219], v[18:21]
	v_mfma_f32_16x16x32_bf16 v[14:17], v[178:181], v[216:219], v[14:17]
	v_mfma_f32_16x16x32_bf16 v[10:13], v[170:173], v[224:227], v[10:13]
	v_mfma_f32_16x16x32_bf16 v[6:9], v[178:181], v[224:227], v[6:9]
	v_mfma_f32_16x16x32_bf16 v[46:49], v[174:177], v[190:193], v[46:49]
	v_mfma_f32_16x16x32_bf16 v[38:41], v[182:185], v[190:193], v[38:41]
	v_mfma_f32_16x16x32_bf16 v[30:33], v[174:177], v[212:215], v[30:33]
	v_mfma_f32_16x16x32_bf16 v[22:25], v[182:185], v[212:215], v[22:25]
	v_mfma_f32_16x16x32_bf16 v[18:21], v[174:177], v[220:223], v[18:21]
	v_mfma_f32_16x16x32_bf16 v[14:17], v[182:185], v[220:223], v[14:17]
	v_mfma_f32_16x16x32_bf16 v[10:13], v[174:177], v[228:231], v[10:13]
	v_mfma_f32_16x16x32_bf16 v[6:9], v[182:185], v[228:231], v[6:9]
	s_barrier
	s_add_i32 s70, 0, 0x18000
	v_add_u32_e32 v4, s70, v148
	s_add_i32 s71, 0, 0x1c000
	ds_read_b128 v[150:153], v4
	ds_read_b128 v[154:157], v4 offset:1024
	ds_read_b128 v[158:161], v4 offset:2048
	ds_read_b128 v[162:165], v4 offset:3072
	v_add_u32_e32 v4, s71, v148
	ds_read_b128 v[170:173], v4
	ds_read_b128 v[174:177], v4 offset:1024
	ds_read_b128 v[178:181], v4 offset:2048
	ds_read_b128 v[182:185], v4 offset:3072
	s_add_u32 s48, s48, s34
	s_addc_u32 s49, s49, 0
	s_mov_b32 m0, s60
	ds_read_b128 v[186:189], v149 offset:32768
	ds_read_b128 v[190:193], v149 offset:33792
	ds_read_b128 v[194:197], v149 offset:34816
	ds_read_b128 v[212:215], v149 offset:35840
	ds_read_b128 v[216:219], v149 offset:36864
	ds_read_b128 v[220:223], v149 offset:37888
	ds_read_b128 v[224:227], v149 offset:38912
	ds_read_b128 v[228:231], v149 offset:39936
	global_load_lds_dwordx4 v140, s[48:49]
	s_mov_b32 m0, s61
	s_nop 0
	global_load_lds_dwordx4 v136, s[48:49]
	s_waitcnt vmcnt(8)
	s_waitcnt lgkmcnt(0)
	s_barrier
	s_waitcnt lgkmcnt(0)
	v_mfma_f32_16x16x32_bf16 v[130:133], v[150:153], v[186:189], v[130:133]
	v_mfma_f32_16x16x32_bf16 v[126:129], v[158:161], v[186:189], v[126:129]
	v_mfma_f32_16x16x32_bf16 v[122:125], v[150:153], v[194:197], v[122:125]
	v_mfma_f32_16x16x32_bf16 v[118:121], v[158:161], v[194:197], v[118:121]
	v_mfma_f32_16x16x32_bf16 v[110:113], v[150:153], v[216:219], v[110:113]
	v_mfma_f32_16x16x32_bf16 v[106:109], v[158:161], v[216:219], v[106:109]
	v_mfma_f32_16x16x32_bf16 v[98:101], v[150:153], v[224:227], v[98:101]
	v_mfma_f32_16x16x32_bf16 v[90:93], v[158:161], v[224:227], v[90:93]
	v_mfma_f32_16x16x32_bf16 v[130:133], v[154:157], v[190:193], v[130:133]
	v_mfma_f32_16x16x32_bf16 v[126:129], v[162:165], v[190:193], v[126:129]
	v_mfma_f32_16x16x32_bf16 v[122:125], v[154:157], v[212:215], v[122:125]
	v_mfma_f32_16x16x32_bf16 v[118:121], v[162:165], v[212:215], v[118:121]
	v_mfma_f32_16x16x32_bf16 v[110:113], v[154:157], v[220:223], v[110:113]
	v_mfma_f32_16x16x32_bf16 v[106:109], v[162:165], v[220:223], v[106:109]
	v_mfma_f32_16x16x32_bf16 v[98:101], v[154:157], v[228:231], v[98:101]
	v_mfma_f32_16x16x32_bf16 v[90:93], v[162:165], v[228:231], v[90:93]
	v_mfma_f32_16x16x32_bf16 v[114:117], v[170:173], v[186:189], v[114:117]
	v_mfma_f32_16x16x32_bf16 v[102:105], v[178:181], v[186:189], v[102:105]
	v_mfma_f32_16x16x32_bf16 v[94:97], v[170:173], v[194:197], v[94:97]
	v_mfma_f32_16x16x32_bf16 v[86:89], v[178:181], v[194:197], v[86:89]
	v_mfma_f32_16x16x32_bf16 v[82:85], v[170:173], v[216:219], v[82:85]
	v_mfma_f32_16x16x32_bf16 v[78:81], v[178:181], v[216:219], v[78:81]
	v_mfma_f32_16x16x32_bf16 v[74:77], v[170:173], v[224:227], v[74:77]
	v_mfma_f32_16x16x32_bf16 v[70:73], v[178:181], v[224:227], v[70:73]
	v_mfma_f32_16x16x32_bf16 v[114:117], v[174:177], v[190:193], v[114:117]
	v_mfma_f32_16x16x32_bf16 v[102:105], v[182:185], v[190:193], v[102:105]
	v_mfma_f32_16x16x32_bf16 v[94:97], v[174:177], v[212:215], v[94:97]
	v_mfma_f32_16x16x32_bf16 v[86:89], v[182:185], v[212:215], v[86:89]
	v_mfma_f32_16x16x32_bf16 v[82:85], v[174:177], v[220:223], v[82:85]
	v_mfma_f32_16x16x32_bf16 v[78:81], v[182:185], v[220:223], v[78:81]
	v_mfma_f32_16x16x32_bf16 v[74:77], v[174:177], v[228:231], v[74:77]
	v_mfma_f32_16x16x32_bf16 v[70:73], v[182:185], v[228:231], v[70:73]
	s_barrier
; #define PG8_STAGE(bufoff, gbase, voff) do { _Pragma("unroll") for (int _i = 0; _i < 2; ++_i) \
;         __builtin_amdgcn_global_load_lds((const unsigned*)((const char*)(gbase) + (voff)[_i]), (LAS unsigned*)(lds + (bufoff) + ldsw + _i * 8192), 16, 0, 0); } while (0)
; #define PG8_LDA(dst, b, h) do { _Pragma("unroll") for (int m = 0; m < 4; ++m) _Pragma("unroll") for (int k = 0; k < 2; ++k) dst[m][k] = *(const LAS bf16x8*)(lds + PG8_SA(b, h) + aoff + m * 2048 + k * 1024); } while (0)
; #define PG8_MMA(ai, bj, At, Bt) do { __builtin_amdgcn_s_setprio(1); _Pragma("unroll") for (int m = 0; m < 4; ++m) _Pragma("unroll") for (int n = 0; n < 2; ++n) _Pragma("unroll") for (int k = 0; k < 2; ++k) \
;         acc[ai][bj][m][n] = __builtin_amdgcn_mfma_f32_16x16x32_bf16(Bt[n][k], At[m][k], acc[ai][bj][m][n], 0, 0, 0); __builtin_amdgcn_s_setprio(0); } while (0)
; #define PG8_WAIT_V(n) asm volatile("s_waitcnt vmcnt(" #n ")" ::: "memory")
; #define PG8_WAIT_L(n) asm volatile("s_waitcnt lgkmcnt(" #n ")" ::: "memory")
; #define PG8_BAR __builtin_amdgcn_s_barrier()
; #define PG8_SCHED __builtin_amdgcn_sched_barrier(0)
; template <class Epi, class Sched>
; __device__ __forceinline__ void gemm_phase(LAS unsigned char* lds, const Gemm g, const Sched& S, const Epi& E) {
;     ...
;             PG8_LDA(At, 1, 1); PG8_STAGE(PG8_SB(1, 0), b3, voffB); PG8_STAGE(PG8_SB(1, 1), b3 + hstepB, voffB); PG8_STAGE(PG8_SA(1, 0), a3, voffA);
;             PG8_WAIT_V(8); PG8_WAIT_L(0); PG8_BAR; PG8_MMA(1, 0, At, B0); PG8_MMA(1, 1, At, B1); PG8_BAR; PG8_SCHED;
;         }
	s_add_i32 s48, s70, s57
	s_add_i32 m0, s48, 0xffffff80
	ds_read_b128 v[186:189], v149 offset:49152
	ds_read_b128 v[190:193], v149 offset:50176
	ds_read_b128 v[194:197], v149 offset:51200
	ds_read_b128 v[212:215], v149 offset:52224
	ds_read_b128 v[216:219], v149 offset:53248
	ds_read_b128 v[220:223], v149 offset:54272
	ds_read_b128 v[224:227], v149 offset:55296
	ds_read_b128 v[228:231], v149 offset:56320
	global_load_lds_dwordx4 v[166:167], off offset:128
	s_add_i32 m0, s48, 0x1f80
	s_add_i32 s48, s71, s57
	global_load_lds_dwordx4 v[236:237], off offset:128
	s_add_i32 m0, s48, 0xffffff80
	s_nop 0
	global_load_lds_dwordx4 v[238:239], off offset:128
	s_add_i32 m0, s48, 0x1f80
	s_nop 0
	global_load_lds_dwordx4 v[240:241], off offset:128
	s_add_i32 m0, s62, 0xffffff80
	s_nop 0
	global_load_lds_dwordx4 v[242:243], off offset:128
	s_add_i32 m0, s63, 0xffffff80
	s_nop 0
	global_load_lds_dwordx4 v[244:245], off offset:128
	s_waitcnt vmcnt(8)
	s_waitcnt lgkmcnt(0)
	s_barrier
	s_waitcnt lgkmcnt(0)
	v_mfma_f32_16x16x32_bf16 v[66:69], v[150:153], v[186:189], v[66:69]
	v_mfma_f32_16x16x32_bf16 v[62:65], v[158:161], v[186:189], v[62:65]
	v_mfma_f32_16x16x32_bf16 v[58:61], v[150:153], v[194:197], v[58:61]
	v_mfma_f32_16x16x32_bf16 v[54:57], v[158:161], v[194:197], v[54:57]
	v_mfma_f32_16x16x32_bf16 v[50:53], v[150:153], v[216:219], v[50:53]
	v_mfma_f32_16x16x32_bf16 v[42:45], v[158:161], v[216:219], v[42:45]
	v_mfma_f32_16x16x32_bf16 v[34:37], v[150:153], v[224:227], v[34:37]
	v_mfma_f32_16x16x32_bf16 v[26:29], v[158:161], v[224:227], v[26:29]
	v_mfma_f32_16x16x32_bf16 v[66:69], v[154:157], v[190:193], v[66:69]
	v_mfma_f32_16x16x32_bf16 v[62:65], v[162:165], v[190:193], v[62:65]
	v_mfma_f32_16x16x32_bf16 v[58:61], v[154:157], v[212:215], v[58:61]
	v_mfma_f32_16x16x32_bf16 v[54:57], v[162:165], v[212:215], v[54:57]
	v_mfma_f32_16x16x32_bf16 v[50:53], v[154:157], v[220:223], v[50:53]
	v_mfma_f32_16x16x32_bf16 v[42:45], v[162:165], v[220:223], v[42:45]
	v_mfma_f32_16x16x32_bf16 v[34:37], v[154:157], v[228:231], v[34:37]
	v_mfma_f32_16x16x32_bf16 v[26:29], v[162:165], v[228:231], v[26:29]
	v_mfma_f32_16x16x32_bf16 v[46:49], v[170:173], v[186:189], v[46:49]
	v_mfma_f32_16x16x32_bf16 v[38:41], v[178:181], v[186:189], v[38:41]
	v_mfma_f32_16x16x32_bf16 v[30:33], v[170:173], v[194:197], v[30:33]
	v_mfma_f32_16x16x32_bf16 v[22:25], v[178:181], v[194:197], v[22:25]
	v_mfma_f32_16x16x32_bf16 v[18:21], v[170:173], v[216:219], v[18:21]
	v_mfma_f32_16x16x32_bf16 v[14:17], v[178:181], v[216:219], v[14:17]
	v_mfma_f32_16x16x32_bf16 v[10:13], v[170:173], v[224:227], v[10:13]
	v_mfma_f32_16x16x32_bf16 v[6:9], v[178:181], v[224:227], v[6:9]
	v_mfma_f32_16x16x32_bf16 v[46:49], v[174:177], v[190:193], v[46:49]
	v_mfma_f32_16x16x32_bf16 v[38:41], v[182:185], v[190:193], v[38:41]
	v_mfma_f32_16x16x32_bf16 v[30:33], v[174:177], v[212:215], v[30:33]
	v_mfma_f32_16x16x32_bf16 v[22:25], v[182:185], v[212:215], v[22:25]
	v_mfma_f32_16x16x32_bf16 v[18:21], v[174:177], v[220:223], v[18:21]
	v_mfma_f32_16x16x32_bf16 v[14:17], v[182:185], v[220:223], v[14:17]
	v_mfma_f32_16x16x32_bf16 v[10:13], v[174:177], v[228:231], v[10:13]
	v_mfma_f32_16x16x32_bf16 v[6:9], v[182:185], v[228:231], v[6:9]
	s_barrier
	s_add_u32 s46, s46, 0x100
	s_addc_u32 s47, s47, 0
	v_lshl_add_u64 v[146:147], v[146:147], 0, s[30:31]
	v_lshl_add_u64 v[2:3], v[2:3], 0, s[30:31]
	s_cmp_ge_u32 s43, s64
	s_mov_b32 s48, s43
	s_cbranch_scc0 .LBB0_1009
	s_and_b64 vcc, exec, s[28:29]
	s_cbranch_vccz .LBB0_1012
	s_barrier
